# P5 SSM pass-A scan rewritten by hand: Bbar-u via v_mfma_f32_32x32x16_bf16 (hi+lo bf16 parts, f32 acc), v_permlane32_swap instead of the LDS transposition, recurrence from registers, double-buffered ac
# speedup vs baseline: 1.0048x; 1.0048x over previous
; __device__ __forceinline__ unsigned cvt_pk_bf16(float lo, float hi) { unsigned r; asm volatile("v_cvt_pk_bf16_f32 %0, %1, %2" : "=v"(r) : "v"(lo), "v"(hi)); return r; }
; __device__ __forceinline__ float bflo(unsigned w) { return __uint_as_float(w << 16); }
; __device__ __forceinline__ float bfhi(unsigned w) { return __uint_as_float(w & 0xffff0000u); }
; #define LAS __attribute__((address_space(3)))
; __device__ __forceinline__ void ssm_load_bfrag(Frame& F, int g, int lane, bf16x8 (&bf)[8]) {
;     const int q = lane >> 4, hs = (q & 1) * 8; const bool lo = q >= 2;
; #pragma unroll
;     for (int cb = 0; cb < 8; ++cb) { const int col = 16 * cb + (lane & 15), p = col & 63, im = col >> 6;
;         const float* src = (const float*)(F.ws + WS_BB) + (size_t)(g * NST + p) * 32 + im * 16 + hs;
;         const f32x4 x0 = *(const f32x4*)src, x1 = *(const f32x4*)(src + 4);
;         float v[8] = {x0.x, x0.y, x0.z, x0.w, x1.x, x1.y, x1.z, x1.w};
;         unsigned w[4];
; #pragma unroll
;         for (int j = 0; j < 4; ++j) { const unsigned hi = cvt_pk_bf16(v[2 * j], v[2 * j + 1]);
;             const unsigned l2 = cvt_pk_bf16(v[2 * j] - bflo(hi), v[2 * j + 1] - bfhi(hi)); w[j] = lo ? l2 : hi; }
;         v4u ww = (v4u){w[0], w[1], w[2], w[3]}; bf[cb] = __builtin_bit_cast(bf16x8, ww); }
; __device__ __forceinline__ void p5_phase(Frame& F) {
;     LAS float* bubuf = (LAS float*)(F.lds + RING_OFF + F.wave * SSM_LDS_W);
;     const bf16* U = (const bf16*)(F.ws + WS_U);
;     const int g = F.gw & (NGRP - 1);
;     bf16x8 bf[8]; ssm_load_bfrag(F, g, F.lane, bf);
;     const f32x2 ab = ((const f32x2*)(F.ws + WS_ABAR))[g * NST + F.lane];
;     bf16x8 nfr[4];
;     { const int bc = F.gw >> 7, r0 = (bc / NCH) * SEQ + (bc % NCH) * TCH;
; #pragma unroll
;       for (int sub = 0; sub < 4; ++sub) nfr[sub] = ssm_load_afrag(U, r0 + 16 * sub, g, F.lane); }
.LBB0_684:
	s_cmp_lt_i32 s8, 6
	s_cselect_b64 s[0:1], -1, 0
	s_cmp_gt_i32 s9, 5
	s_cselect_b64 s[2:3], -1, 0
	s_and_b64 s[0:1], s[0:1], s[2:3]
	s_andn2_b64 vcc, exec, s[0:1]
	v_lshlrev_b32_e32 v1, 7, v0
	s_cbranch_vccnz .LBB0_783
	s_waitcnt vmcnt(0)
	s_and_b32 s56, s88, 0x7f
	v_and_b32_e32 v177, 31, v198
	v_lshrrev_b32_e32 v2, 5, v198
	v_lshlrev_b32_e32 v3, 7, v177
	v_lshl_or_b32 v3, v2, 5, v3
	s_lshl_b32 s57, s56, 13
	s_add_u32 s50, s96, 0x120000
	s_addc_u32 s51, s97, 0
	s_add_u32 s50, s50, s57
	s_addc_u32 s51, s51, 0
	s_add_u32 s52, s50, 0x1000
	s_addc_u32 s53, s51, 0
	global_load_dwordx4 v[16:19], v3, s[50:51]
	global_load_dwordx4 v[20:23], v3, s[50:51] offset:16
	global_load_dwordx4 v[24:27], v3, s[52:53]
	global_load_dwordx4 v[28:31], v3, s[52:53] offset:16
	global_load_dwordx4 v[32:35], v3, s[50:51] offset:64
	global_load_dwordx4 v[36:39], v3, s[50:51] offset:80
	global_load_dwordx4 v[40:43], v3, s[52:53] offset:64
	global_load_dwordx4 v[44:47], v3, s[52:53] offset:80
	v_lshlrev_b32_e32 v7, 3, v198
	v_lshl_or_b32 v4, s56, 9, v7
	s_add_u32 s58, s96, 0x100000
	s_addc_u32 s59, s97, 0
	global_load_dwordx2 v[8:9], v4, s[58:59]
	v_lshlrev_b32_e32 v5, 12, v177
	v_lshl_or_b32 v5, v2, 4, v5
	v_add_u32_e32 v6, 0x20000, v5
	s_lshr_b32 s54, s88, 7
	s_lshl_b32 s54, s54, 18
	s_lshl_b32 s60, s56, 5
	s_add_u32 s54, s54, s60
	s_add_u32 s54, s54, 0x39600000
	s_add_u32 s54, s96, s54
	s_addc_u32 s55, s97, 0
	s_lshl_b32 s48, s88, 9
	s_add_u32 s48, s48, 0x400000
	s_add_u32 s48, s96, s48
	s_addc_u32 s49, s97, 0
	global_load_dwordx4 v[80:83], v5, s[54:55]
	global_load_dwordx4 v[84:87], v6, s[54:55]
	s_add_u32 s54, s54, 0x400000
	s_addc_u32 s55, s55, 0
	global_load_dwordx4 v[88:91], v5, s[54:55]
	global_load_dwordx4 v[92:95], v6, s[54:55]
	s_add_u32 s54, s54, 0x400000
	s_addc_u32 s55, s55, 0
	global_load_dwordx4 v[96:99], v5, s[54:55]
	global_load_dwordx4 v[100:103], v6, s[54:55]
	s_add_u32 s54, s54, 0x400000
	s_addc_u32 s55, s55, 0
	global_load_dwordx4 v[104:107], v5, s[54:55]
	global_load_dwordx4 v[108:111], v6, s[54:55]
	s_add_u32 s54, s54, 0x400000
	s_addc_u32 s55, s55, 0
	s_waitcnt vmcnt(15)
	v_cvt_pk_bf16_f32 v48, v16, v17
	s_nop 0
	v_lshlrev_b32_e32 v14, 16, v48
	v_and_b32_e32 v15, 0xffff0000, v48
	v_sub_f32_e32 v14, v16, v14
	v_sub_f32_e32 v15, v17, v15
	v_cvt_pk_bf16_f32 v64, v14, v15
	v_cvt_pk_bf16_f32 v49, v18, v19
	s_nop 0
	v_lshlrev_b32_e32 v14, 16, v49
	v_and_b32_e32 v15, 0xffff0000, v49
	v_sub_f32_e32 v14, v18, v14
	v_sub_f32_e32 v15, v19, v15
	v_cvt_pk_bf16_f32 v65, v14, v15
	v_cvt_pk_bf16_f32 v50, v20, v21
	s_nop 0
	v_lshlrev_b32_e32 v14, 16, v50
	v_and_b32_e32 v15, 0xffff0000, v50
	v_sub_f32_e32 v14, v20, v14
	v_sub_f32_e32 v15, v21, v15
	v_cvt_pk_bf16_f32 v66, v14, v15
	v_cvt_pk_bf16_f32 v51, v22, v23
	s_nop 0
	v_lshlrev_b32_e32 v14, 16, v51
	v_and_b32_e32 v15, 0xffff0000, v51
	v_sub_f32_e32 v14, v22, v14
	v_sub_f32_e32 v15, v23, v15
	v_cvt_pk_bf16_f32 v67, v14, v15
	s_waitcnt vmcnt(13)
	v_cvt_pk_bf16_f32 v52, v24, v25
	s_nop 0
	v_lshlrev_b32_e32 v14, 16, v52
	v_and_b32_e32 v15, 0xffff0000, v52
	v_sub_f32_e32 v14, v24, v14
	v_sub_f32_e32 v15, v25, v15
	v_cvt_pk_bf16_f32 v68, v14, v15
	v_cvt_pk_bf16_f32 v53, v26, v27
	s_nop 0
	v_lshlrev_b32_e32 v14, 16, v53
	v_and_b32_e32 v15, 0xffff0000, v53
	v_sub_f32_e32 v14, v26, v14
	v_sub_f32_e32 v15, v27, v15
	v_cvt_pk_bf16_f32 v69, v14, v15
	v_cvt_pk_bf16_f32 v54, v28, v29
	s_nop 0
	v_lshlrev_b32_e32 v14, 16, v54
	v_and_b32_e32 v15, 0xffff0000, v54
	v_sub_f32_e32 v14, v28, v14
	v_sub_f32_e32 v15, v29, v15
	v_cvt_pk_bf16_f32 v70, v14, v15
	v_cvt_pk_bf16_f32 v55, v30, v31
	s_nop 0
	v_lshlrev_b32_e32 v14, 16, v55
	v_and_b32_e32 v15, 0xffff0000, v55
	v_sub_f32_e32 v14, v30, v14
	v_sub_f32_e32 v15, v31, v15
	v_cvt_pk_bf16_f32 v71, v14, v15
	s_waitcnt vmcnt(11)
	v_cvt_pk_bf16_f32 v56, v32, v33
	s_nop 0
	v_lshlrev_b32_e32 v14, 16, v56
	v_and_b32_e32 v15, 0xffff0000, v56
	v_sub_f32_e32 v14, v32, v14
	v_sub_f32_e32 v15, v33, v15
	v_cvt_pk_bf16_f32 v72, v14, v15
	v_cvt_pk_bf16_f32 v57, v34, v35
	s_nop 0
	v_lshlrev_b32_e32 v14, 16, v57
	v_and_b32_e32 v15, 0xffff0000, v57
	v_sub_f32_e32 v14, v34, v14
	v_sub_f32_e32 v15, v35, v15
	v_cvt_pk_bf16_f32 v73, v14, v15
	v_cvt_pk_bf16_f32 v58, v36, v37
	s_nop 0
	v_lshlrev_b32_e32 v14, 16, v58
	v_and_b32_e32 v15, 0xffff0000, v58
	v_sub_f32_e32 v14, v36, v14
	v_sub_f32_e32 v15, v37, v15
	v_cvt_pk_bf16_f32 v74, v14, v15
	v_cvt_pk_bf16_f32 v59, v38, v39
	s_nop 0
	v_lshlrev_b32_e32 v14, 16, v59
	v_and_b32_e32 v15, 0xffff0000, v59
	v_sub_f32_e32 v14, v38, v14
	v_sub_f32_e32 v15, v39, v15
	v_cvt_pk_bf16_f32 v75, v14, v15
	s_waitcnt vmcnt(9)
	v_cvt_pk_bf16_f32 v60, v40, v41
	s_nop 0
	v_lshlrev_b32_e32 v14, 16, v60
	v_and_b32_e32 v15, 0xffff0000, v60
	v_sub_f32_e32 v14, v40, v14
	v_sub_f32_e32 v15, v41, v15
	v_cvt_pk_bf16_f32 v76, v14, v15
	v_cvt_pk_bf16_f32 v61, v42, v43
	s_nop 0
	v_lshlrev_b32_e32 v14, 16, v61
	v_and_b32_e32 v15, 0xffff0000, v61
	v_sub_f32_e32 v14, v42, v14
	v_sub_f32_e32 v15, v43, v15
	v_cvt_pk_bf16_f32 v77, v14, v15
	v_cvt_pk_bf16_f32 v62, v44, v45
	s_nop 0
	v_lshlrev_b32_e32 v14, 16, v62
	v_and_b32_e32 v15, 0xffff0000, v62
	v_sub_f32_e32 v14, v44, v14
	v_sub_f32_e32 v15, v45, v15
	v_cvt_pk_bf16_f32 v78, v14, v15
	v_cvt_pk_bf16_f32 v63, v46, v47
	s_nop 0
	v_lshlrev_b32_e32 v14, 16, v63
	v_and_b32_e32 v15, 0xffff0000, v63
	v_sub_f32_e32 v14, v46, v14
	v_sub_f32_e32 v15, v47, v15
	v_cvt_pk_bf16_f32 v79, v14, v15
	s_waitcnt vmcnt(8)
	v_xor_b32_e32 v10, 0x80000000, v9
	s_nop 1
	s_waitcnt vmcnt(7)
; #define LAS __attribute__((address_space(3)))
; #define LDS_WAIT() asm volatile("s_waitcnt lgkmcnt(0)" ::: "memory")
; #define MFMA_PIN(a, b) do { __builtin_amdgcn_sched_barrier(0); asm volatile("" :: "v"(a), "v"(b)); } while (0)
; #define MFMA_SETTLE() do { __builtin_amdgcn_sched_barrier(0); asm volatile("s_nop 15"); __builtin_amdgcn_sched_barrier(0); } while (0)
; __device__ __forceinline__ void ssm_bu16(const bf16x8 afr, const bf16x8 (&bf)[8], LAS float* bubuf, int lane) {
;     LAS float* wp = bubuf + (4 * (lane >> 4)) * BUP + (lane & 15);
;     f32x4 d[8];
; #pragma unroll
;     for (int cb = 0; cb < 8; ++cb) { d[cb] = __builtin_amdgcn_mfma_f32_16x16x32_bf16(afr, bf[cb], (f32x4){0.f, 0.f, 0.f, 0.f}, 0, 0, 0); MFMA_PIN(afr, bf[cb]); }
;     MFMA_SETTLE();
; __device__ __forceinline__ void p5_phase(Frame& F) {
;     ...
;         float sr = 0.f, si = 0.f;
; #pragma unroll
;         for (int sub = 0; sub < 4; ++sub) {
;             ssm_bu16(afr[sub], bf, bubuf, F.lane);
; #pragma unroll
;             for (int tt = 0; tt < 16; ++tt) { const float bur = bubuf[tt * BUP + F.lane], bui = bubuf[tt * BUP + 64 + F.lane];
;                 const float nr = fmaf(ab.x, sr, fmaf(-ab.y, si, bur)), ni = fmaf(ab.x, si, fmaf(ab.y, sr, bui)); sr = nr; si = ni; }
;             LDS_WAIT(); asm volatile("" ::: "memory");
;         }
	v_mfma_f32_32x32x16_bf16 v[112:127], v[80:83], v[48:51], 0
	v_mfma_f32_32x32x16_bf16 v[128:143], v[80:83], v[52:55], 0
	v_mfma_f32_32x32x16_bf16 v[144:159], v[80:83], v[56:59], 0
	v_mfma_f32_32x32x16_bf16 v[160:175], v[80:83], v[60:63], 0
	v_mfma_f32_32x32x16_bf16 v[112:127], v[80:83], v[64:67], v[112:127]
	v_mfma_f32_32x32x16_bf16 v[128:143], v[80:83], v[68:71], v[128:143]
	v_mfma_f32_32x32x16_bf16 v[144:159], v[80:83], v[72:75], v[144:159]
	v_mfma_f32_32x32x16_bf16 v[160:175], v[80:83], v[76:79], v[160:175]
	v_mov_b32_e32 v12, 0
	v_mov_b32_e32 v13, 0
	s_waitcnt vmcnt(6)
	v_mfma_f32_32x32x16_bf16 v[16:31], v[84:87], v[48:51], 0
	v_mfma_f32_32x32x16_bf16 v[32:47], v[84:87], v[52:55], 0
	v_mfma_f32_32x32x16_bf16 v[200:215], v[84:87], v[56:59], 0
	v_mfma_f32_32x32x16_bf16 v[216:231], v[84:87], v[60:63], 0
	v_mfma_f32_32x32x16_bf16 v[16:31], v[84:87], v[64:67], v[16:31]
	v_mfma_f32_32x32x16_bf16 v[32:47], v[84:87], v[68:71], v[32:47]
	v_mfma_f32_32x32x16_bf16 v[200:215], v[84:87], v[72:75], v[200:215]
	v_mfma_f32_32x32x16_bf16 v[216:231], v[84:87], v[76:79], v[216:231]
	s_nop 15
	s_nop 3
	v_permlane32_swap_b32_e32 v112, v128
	v_permlane32_swap_b32_e32 v144, v160
	v_permlane32_swap_b32_e32 v113, v129
	v_permlane32_swap_b32_e32 v145, v161
	v_permlane32_swap_b32_e32 v114, v130
	v_permlane32_swap_b32_e32 v146, v162
	v_permlane32_swap_b32_e32 v115, v131
	v_permlane32_swap_b32_e32 v147, v163
	v_permlane32_swap_b32_e32 v116, v132
	v_permlane32_swap_b32_e32 v148, v164
	v_permlane32_swap_b32_e32 v117, v133
	v_permlane32_swap_b32_e32 v149, v165
	v_permlane32_swap_b32_e32 v118, v134
	v_permlane32_swap_b32_e32 v150, v166
	v_permlane32_swap_b32_e32 v119, v135
	v_permlane32_swap_b32_e32 v151, v167
	v_permlane32_swap_b32_e32 v120, v136
	v_permlane32_swap_b32_e32 v152, v168
	v_permlane32_swap_b32_e32 v121, v137
	v_permlane32_swap_b32_e32 v153, v169
	v_permlane32_swap_b32_e32 v122, v138
	v_permlane32_swap_b32_e32 v154, v170
	v_permlane32_swap_b32_e32 v123, v139
	v_permlane32_swap_b32_e32 v155, v171
	v_permlane32_swap_b32_e32 v124, v140
	v_permlane32_swap_b32_e32 v156, v172
	v_permlane32_swap_b32_e32 v125, v141
	v_permlane32_swap_b32_e32 v157, v173
	v_permlane32_swap_b32_e32 v126, v142
	v_permlane32_swap_b32_e32 v158, v174
	v_permlane32_swap_b32_e32 v127, v143
	v_permlane32_swap_b32_e32 v159, v175
	v_fmac_f32_e32 v112, v10, v13
	v_fmac_f32_e32 v144, v9, v12
	v_fma_f32 v12, v8, v12, v112
	v_fma_f32 v13, v8, v13, v144
	v_fmac_f32_e32 v113, v10, v13
	v_fmac_f32_e32 v145, v9, v12
	v_fma_f32 v12, v8, v12, v113
	v_fma_f32 v13, v8, v13, v145
	v_fmac_f32_e32 v114, v10, v13
	v_fmac_f32_e32 v146, v9, v12
	v_fma_f32 v12, v8, v12, v114
	v_fma_f32 v13, v8, v13, v146
	v_fmac_f32_e32 v115, v10, v13
	v_fmac_f32_e32 v147, v9, v12
	v_fma_f32 v12, v8, v12, v115
	v_fma_f32 v13, v8, v13, v147
	v_fmac_f32_e32 v128, v10, v13
	v_fmac_f32_e32 v160, v9, v12
	v_fma_f32 v12, v8, v12, v128
	v_fma_f32 v13, v8, v13, v160
	v_fmac_f32_e32 v129, v10, v13
	v_fmac_f32_e32 v161, v9, v12
	v_fma_f32 v12, v8, v12, v129
	v_fma_f32 v13, v8, v13, v161
	v_fmac_f32_e32 v130, v10, v13
	v_fmac_f32_e32 v162, v9, v12
	v_fma_f32 v12, v8, v12, v130
	v_fma_f32 v13, v8, v13, v162
	v_fmac_f32_e32 v131, v10, v13
	v_fmac_f32_e32 v163, v9, v12
	v_fma_f32 v12, v8, v12, v131
	v_fma_f32 v13, v8, v13, v163
	v_fmac_f32_e32 v116, v10, v13
	v_fmac_f32_e32 v148, v9, v12
	v_fma_f32 v12, v8, v12, v116
	v_fma_f32 v13, v8, v13, v148
	v_fmac_f32_e32 v117, v10, v13
	v_fmac_f32_e32 v149, v9, v12
	v_fma_f32 v12, v8, v12, v117
	v_fma_f32 v13, v8, v13, v149
	v_fmac_f32_e32 v118, v10, v13
	v_fmac_f32_e32 v150, v9, v12
	v_fma_f32 v12, v8, v12, v118
	v_fma_f32 v13, v8, v13, v150
	v_fmac_f32_e32 v119, v10, v13
	v_fmac_f32_e32 v151, v9, v12
	v_fma_f32 v12, v8, v12, v119
	v_fma_f32 v13, v8, v13, v151
	v_fmac_f32_e32 v132, v10, v13
	v_fmac_f32_e32 v164, v9, v12
	v_fma_f32 v12, v8, v12, v132
	v_fma_f32 v13, v8, v13, v164
	v_fmac_f32_e32 v133, v10, v13
	v_fmac_f32_e32 v165, v9, v12
	v_fma_f32 v12, v8, v12, v133
	v_fma_f32 v13, v8, v13, v165
	v_fmac_f32_e32 v134, v10, v13
	v_fmac_f32_e32 v166, v9, v12
	v_fma_f32 v12, v8, v12, v134
	v_fma_f32 v13, v8, v13, v166
	v_fmac_f32_e32 v135, v10, v13
	v_fmac_f32_e32 v167, v9, v12
	v_fma_f32 v12, v8, v12, v135
	v_fma_f32 v13, v8, v13, v167
	v_fmac_f32_e32 v120, v10, v13
	v_fmac_f32_e32 v152, v9, v12
	v_fma_f32 v12, v8, v12, v120
	v_fma_f32 v13, v8, v13, v152
	v_fmac_f32_e32 v121, v10, v13
	v_fmac_f32_e32 v153, v9, v12
	v_fma_f32 v12, v8, v12, v121
	v_fma_f32 v13, v8, v13, v153
	v_fmac_f32_e32 v122, v10, v13
	v_fmac_f32_e32 v154, v9, v12
	v_fma_f32 v12, v8, v12, v122
	v_fma_f32 v13, v8, v13, v154
	v_fmac_f32_e32 v123, v10, v13
	v_fmac_f32_e32 v155, v9, v12
	v_fma_f32 v12, v8, v12, v123
	v_fma_f32 v13, v8, v13, v155
	v_fmac_f32_e32 v136, v10, v13
	v_fmac_f32_e32 v168, v9, v12
	v_fma_f32 v12, v8, v12, v136
	v_fma_f32 v13, v8, v13, v168
	v_fmac_f32_e32 v137, v10, v13
	v_fmac_f32_e32 v169, v9, v12
	v_fma_f32 v12, v8, v12, v137
	v_fma_f32 v13, v8, v13, v169
	v_fmac_f32_e32 v138, v10, v13
	v_fmac_f32_e32 v170, v9, v12
	v_fma_f32 v12, v8, v12, v138
	v_fma_f32 v13, v8, v13, v170
	v_fmac_f32_e32 v139, v10, v13
	v_fmac_f32_e32 v171, v9, v12
	v_fma_f32 v12, v8, v12, v139
	v_fma_f32 v13, v8, v13, v171
	v_fmac_f32_e32 v124, v10, v13
	v_fmac_f32_e32 v156, v9, v12
	v_fma_f32 v12, v8, v12, v124
	v_fma_f32 v13, v8, v13, v156
	v_fmac_f32_e32 v125, v10, v13
	v_fmac_f32_e32 v157, v9, v12
	v_fma_f32 v12, v8, v12, v125
	v_fma_f32 v13, v8, v13, v157
	v_fmac_f32_e32 v126, v10, v13
	v_fmac_f32_e32 v158, v9, v12
	v_fma_f32 v12, v8, v12, v126
	v_fma_f32 v13, v8, v13, v158
	v_fmac_f32_e32 v127, v10, v13
	v_fmac_f32_e32 v159, v9, v12
	v_fma_f32 v12, v8, v12, v127
	v_fma_f32 v13, v8, v13, v159
	v_fmac_f32_e32 v140, v10, v13
	v_fmac_f32_e32 v172, v9, v12
	v_fma_f32 v12, v8, v12, v140
	v_fma_f32 v13, v8, v13, v172
	v_fmac_f32_e32 v141, v10, v13
	v_fmac_f32_e32 v173, v9, v12
	v_fma_f32 v12, v8, v12, v141
	v_fma_f32 v13, v8, v13, v173
	v_fmac_f32_e32 v142, v10, v13
	v_fmac_f32_e32 v174, v9, v12
	v_fma_f32 v12, v8, v12, v142
	v_fma_f32 v13, v8, v13, v174
	v_fmac_f32_e32 v143, v10, v13
	v_fmac_f32_e32 v175, v9, v12
	v_fma_f32 v12, v8, v12, v143
	v_fma_f32 v13, v8, v13, v175
	s_waitcnt vmcnt(5)
; #define LDS_WAIT() asm volatile("s_waitcnt lgkmcnt(0)" ::: "memory")
; __device__ __forceinline__ void p5_phase(Frame& F) {
;     ...
;     for (int it = F.gw; it < NB * NCH * NGRP; it += F.ngw) {
;         bf16x8 afr[4];
; #pragma unroll
;         for (int sub = 0; sub < 4; ++sub) afr[sub] = nfr[sub];
;         if (it + F.ngw < NB * NCH * NGRP) { const int bc = (it + F.ngw) >> 7, r0 = (bc / NCH) * SEQ + (bc % NCH) * TCH;
; #pragma unroll
;             for (int sub = 0; sub < 4; ++sub) nfr[sub] = ssm_load_afrag(U, r0 + 16 * sub, g, F.lane); }
;         float sr = 0.f, si = 0.f;
; #pragma unroll
;         for (int sub = 0; sub < 4; ++sub) {
;             ssm_bu16(afr[sub], bf, bubuf, F.lane);
; #pragma unroll
;             for (int tt = 0; tt < 16; ++tt) { const float bur = bubuf[tt * BUP + F.lane], bui = bubuf[tt * BUP + 64 + F.lane];
;                 const float nr = fmaf(ab.x, sr, fmaf(-ab.y, si, bur)), ni = fmaf(ab.x, si, fmaf(ab.y, sr, bui)); sr = nr; si = ni; }
;             LDS_WAIT(); asm volatile("" ::: "memory");
;         }
;         ((f32x2*)(F.ws + WS_E))[(size_t)it * NST + F.lane] = (f32x2){sr, si};
	v_mfma_f32_32x32x16_bf16 v[112:127], v[88:91], v[48:51], 0
	v_mfma_f32_32x32x16_bf16 v[128:143], v[88:91], v[52:55], 0
	v_mfma_f32_32x32x16_bf16 v[144:159], v[88:91], v[56:59], 0
	v_mfma_f32_32x32x16_bf16 v[160:175], v[88:91], v[60:63], 0
	v_mfma_f32_32x32x16_bf16 v[112:127], v[88:91], v[64:67], v[112:127]
	v_mfma_f32_32x32x16_bf16 v[128:143], v[88:91], v[68:71], v[128:143]
	v_mfma_f32_32x32x16_bf16 v[144:159], v[88:91], v[72:75], v[144:159]
	v_mfma_f32_32x32x16_bf16 v[160:175], v[88:91], v[76:79], v[160:175]
	s_nop 3
	v_permlane32_swap_b32_e32 v16, v32
	v_permlane32_swap_b32_e32 v200, v216
	v_permlane32_swap_b32_e32 v17, v33
	v_permlane32_swap_b32_e32 v201, v217
	v_permlane32_swap_b32_e32 v18, v34
	v_permlane32_swap_b32_e32 v202, v218
	v_permlane32_swap_b32_e32 v19, v35
	v_permlane32_swap_b32_e32 v203, v219
	v_permlane32_swap_b32_e32 v20, v36
	v_permlane32_swap_b32_e32 v204, v220
	v_permlane32_swap_b32_e32 v21, v37
	v_permlane32_swap_b32_e32 v205, v221
	v_permlane32_swap_b32_e32 v22, v38
	v_permlane32_swap_b32_e32 v206, v222
	v_permlane32_swap_b32_e32 v23, v39
	v_permlane32_swap_b32_e32 v207, v223
	v_permlane32_swap_b32_e32 v24, v40
	v_permlane32_swap_b32_e32 v208, v224
	v_permlane32_swap_b32_e32 v25, v41
	v_permlane32_swap_b32_e32 v209, v225
	v_permlane32_swap_b32_e32 v26, v42
	v_permlane32_swap_b32_e32 v210, v226
	v_permlane32_swap_b32_e32 v27, v43
	v_permlane32_swap_b32_e32 v211, v227
	v_permlane32_swap_b32_e32 v28, v44
	v_permlane32_swap_b32_e32 v212, v228
	v_permlane32_swap_b32_e32 v29, v45
	v_permlane32_swap_b32_e32 v213, v229
	v_permlane32_swap_b32_e32 v30, v46
	v_permlane32_swap_b32_e32 v214, v230
	v_permlane32_swap_b32_e32 v31, v47
	v_permlane32_swap_b32_e32 v215, v231
	v_fmac_f32_e32 v16, v10, v13
	v_fmac_f32_e32 v200, v9, v12
	v_fma_f32 v12, v8, v12, v16
	v_fma_f32 v13, v8, v13, v200
	v_fmac_f32_e32 v17, v10, v13
	v_fmac_f32_e32 v201, v9, v12
	v_fma_f32 v12, v8, v12, v17
	v_fma_f32 v13, v8, v13, v201
	v_fmac_f32_e32 v18, v10, v13
	v_fmac_f32_e32 v202, v9, v12
	v_fma_f32 v12, v8, v12, v18
	v_fma_f32 v13, v8, v13, v202
	v_fmac_f32_e32 v19, v10, v13
	v_fmac_f32_e32 v203, v9, v12
	v_fma_f32 v12, v8, v12, v19
	v_fma_f32 v13, v8, v13, v203
	v_fmac_f32_e32 v32, v10, v13
	v_fmac_f32_e32 v216, v9, v12
	v_fma_f32 v12, v8, v12, v32
	v_fma_f32 v13, v8, v13, v216
	v_fmac_f32_e32 v33, v10, v13
	v_fmac_f32_e32 v217, v9, v12
	v_fma_f32 v12, v8, v12, v33
	v_fma_f32 v13, v8, v13, v217
	v_fmac_f32_e32 v34, v10, v13
	v_fmac_f32_e32 v218, v9, v12
	v_fma_f32 v12, v8, v12, v34
	v_fma_f32 v13, v8, v13, v218
	v_fmac_f32_e32 v35, v10, v13
	v_fmac_f32_e32 v219, v9, v12
	v_fma_f32 v12, v8, v12, v35
	v_fma_f32 v13, v8, v13, v219
	v_fmac_f32_e32 v20, v10, v13
	v_fmac_f32_e32 v204, v9, v12
	v_fma_f32 v12, v8, v12, v20
	v_fma_f32 v13, v8, v13, v204
	v_fmac_f32_e32 v21, v10, v13
	v_fmac_f32_e32 v205, v9, v12
	v_fma_f32 v12, v8, v12, v21
	v_fma_f32 v13, v8, v13, v205
	v_fmac_f32_e32 v22, v10, v13
	v_fmac_f32_e32 v206, v9, v12
	v_fma_f32 v12, v8, v12, v22
	v_fma_f32 v13, v8, v13, v206
	v_fmac_f32_e32 v23, v10, v13
	v_fmac_f32_e32 v207, v9, v12
	v_fma_f32 v12, v8, v12, v23
	v_fma_f32 v13, v8, v13, v207
	v_fmac_f32_e32 v36, v10, v13
	v_fmac_f32_e32 v220, v9, v12
	v_fma_f32 v12, v8, v12, v36
	v_fma_f32 v13, v8, v13, v220
	v_fmac_f32_e32 v37, v10, v13
	v_fmac_f32_e32 v221, v9, v12
	v_fma_f32 v12, v8, v12, v37
	v_fma_f32 v13, v8, v13, v221
	v_fmac_f32_e32 v38, v10, v13
	v_fmac_f32_e32 v222, v9, v12
	v_fma_f32 v12, v8, v12, v38
	v_fma_f32 v13, v8, v13, v222
	v_fmac_f32_e32 v39, v10, v13
	v_fmac_f32_e32 v223, v9, v12
	v_fma_f32 v12, v8, v12, v39
	v_fma_f32 v13, v8, v13, v223
	v_fmac_f32_e32 v24, v10, v13
	v_fmac_f32_e32 v208, v9, v12
	v_fma_f32 v12, v8, v12, v24
	v_fma_f32 v13, v8, v13, v208
	v_fmac_f32_e32 v25, v10, v13
	v_fmac_f32_e32 v209, v9, v12
	v_fma_f32 v12, v8, v12, v25
	v_fma_f32 v13, v8, v13, v209
	v_fmac_f32_e32 v26, v10, v13
	v_fmac_f32_e32 v210, v9, v12
	v_fma_f32 v12, v8, v12, v26
	v_fma_f32 v13, v8, v13, v210
	v_fmac_f32_e32 v27, v10, v13
	v_fmac_f32_e32 v211, v9, v12
	v_fma_f32 v12, v8, v12, v27
	v_fma_f32 v13, v8, v13, v211
	v_fmac_f32_e32 v40, v10, v13
	v_fmac_f32_e32 v224, v9, v12
	v_fma_f32 v12, v8, v12, v40
	v_fma_f32 v13, v8, v13, v224
	v_fmac_f32_e32 v41, v10, v13
	v_fmac_f32_e32 v225, v9, v12
	v_fma_f32 v12, v8, v12, v41
	v_fma_f32 v13, v8, v13, v225
	v_fmac_f32_e32 v42, v10, v13
	v_fmac_f32_e32 v226, v9, v12
	v_fma_f32 v12, v8, v12, v42
	v_fma_f32 v13, v8, v13, v226
	v_fmac_f32_e32 v43, v10, v13
	v_fmac_f32_e32 v227, v9, v12
	v_fma_f32 v12, v8, v12, v43
	v_fma_f32 v13, v8, v13, v227
	v_fmac_f32_e32 v28, v10, v13
	v_fmac_f32_e32 v212, v9, v12
	v_fma_f32 v12, v8, v12, v28
	v_fma_f32 v13, v8, v13, v212
	v_fmac_f32_e32 v29, v10, v13
	v_fmac_f32_e32 v213, v9, v12
	v_fma_f32 v12, v8, v12, v29
	v_fma_f32 v13, v8, v13, v213
	v_fmac_f32_e32 v30, v10, v13
	v_fmac_f32_e32 v214, v9, v12
	v_fma_f32 v12, v8, v12, v30
	v_fma_f32 v13, v8, v13, v214
	v_fmac_f32_e32 v31, v10, v13
	v_fmac_f32_e32 v215, v9, v12
	v_fma_f32 v12, v8, v12, v31
	v_fma_f32 v13, v8, v13, v215
	v_fmac_f32_e32 v44, v10, v13
	v_fmac_f32_e32 v228, v9, v12
	v_fma_f32 v12, v8, v12, v44
	v_fma_f32 v13, v8, v13, v228
	v_fmac_f32_e32 v45, v10, v13
	v_fmac_f32_e32 v229, v9, v12
	v_fma_f32 v12, v8, v12, v45
	v_fma_f32 v13, v8, v13, v229
	v_fmac_f32_e32 v46, v10, v13
	v_fmac_f32_e32 v230, v9, v12
	v_fma_f32 v12, v8, v12, v46
	v_fma_f32 v13, v8, v13, v230
	v_fmac_f32_e32 v47, v10, v13
	v_fmac_f32_e32 v231, v9, v12
	v_fma_f32 v12, v8, v12, v47
	v_fma_f32 v13, v8, v13, v231
	s_nop 0
	global_store_dwordx2 v7, v[12:13], s[48:49]
	s_add_u32 s48, s48, 0x100000
	s_addc_u32 s49, s49, 0
	global_load_dwordx4 v[80:83], v5, s[54:55]
	global_load_dwordx4 v[84:87], v6, s[54:55]
	s_add_u32 s54, s54, 0x400000
	s_addc_u32 s55, s55, 0
	v_mov_b32_e32 v12, 0
	v_mov_b32_e32 v13, 0
	s_waitcnt vmcnt(7)
; #define LDS_WAIT() asm volatile("s_waitcnt lgkmcnt(0)" ::: "memory")
; __device__ __forceinline__ void p5_phase(Frame& F) {
;     ...
;         float sr = 0.f, si = 0.f;
; #pragma unroll
;         for (int sub = 0; sub < 4; ++sub) {
;             ssm_bu16(afr[sub], bf, bubuf, F.lane);
; #pragma unroll
;             for (int tt = 0; tt < 16; ++tt) { const float bur = bubuf[tt * BUP + F.lane], bui = bubuf[tt * BUP + 64 + F.lane];
;                 const float nr = fmaf(ab.x, sr, fmaf(-ab.y, si, bur)), ni = fmaf(ab.x, si, fmaf(ab.y, sr, bui)); sr = nr; si = ni; }
;             LDS_WAIT(); asm volatile("" ::: "memory");
;         }
	v_mfma_f32_32x32x16_bf16 v[16:31], v[92:95], v[48:51], 0
	v_mfma_f32_32x32x16_bf16 v[32:47], v[92:95], v[52:55], 0
	v_mfma_f32_32x32x16_bf16 v[200:215], v[92:95], v[56:59], 0
	v_mfma_f32_32x32x16_bf16 v[216:231], v[92:95], v[60:63], 0
	v_mfma_f32_32x32x16_bf16 v[16:31], v[92:95], v[64:67], v[16:31]
	v_mfma_f32_32x32x16_bf16 v[32:47], v[92:95], v[68:71], v[32:47]
	v_mfma_f32_32x32x16_bf16 v[200:215], v[92:95], v[72:75], v[200:215]
	v_mfma_f32_32x32x16_bf16 v[216:231], v[92:95], v[76:79], v[216:231]
	s_nop 3
	v_permlane32_swap_b32_e32 v112, v128
	v_permlane32_swap_b32_e32 v144, v160
	v_permlane32_swap_b32_e32 v113, v129
	v_permlane32_swap_b32_e32 v145, v161
	v_permlane32_swap_b32_e32 v114, v130
	v_permlane32_swap_b32_e32 v146, v162
	v_permlane32_swap_b32_e32 v115, v131
	v_permlane32_swap_b32_e32 v147, v163
	v_permlane32_swap_b32_e32 v116, v132
	v_permlane32_swap_b32_e32 v148, v164
	v_permlane32_swap_b32_e32 v117, v133
	v_permlane32_swap_b32_e32 v149, v165
	v_permlane32_swap_b32_e32 v118, v134
	v_permlane32_swap_b32_e32 v150, v166
	v_permlane32_swap_b32_e32 v119, v135
	v_permlane32_swap_b32_e32 v151, v167
	v_permlane32_swap_b32_e32 v120, v136
	v_permlane32_swap_b32_e32 v152, v168
	v_permlane32_swap_b32_e32 v121, v137
	v_permlane32_swap_b32_e32 v153, v169
	v_permlane32_swap_b32_e32 v122, v138
	v_permlane32_swap_b32_e32 v154, v170
	v_permlane32_swap_b32_e32 v123, v139
	v_permlane32_swap_b32_e32 v155, v171
	v_permlane32_swap_b32_e32 v124, v140
	v_permlane32_swap_b32_e32 v156, v172
	v_permlane32_swap_b32_e32 v125, v141
	v_permlane32_swap_b32_e32 v157, v173
	v_permlane32_swap_b32_e32 v126, v142
	v_permlane32_swap_b32_e32 v158, v174
	v_permlane32_swap_b32_e32 v127, v143
	v_permlane32_swap_b32_e32 v159, v175
	v_fmac_f32_e32 v112, v10, v13
	v_fmac_f32_e32 v144, v9, v12
	v_fma_f32 v12, v8, v12, v112
	v_fma_f32 v13, v8, v13, v144
	v_fmac_f32_e32 v113, v10, v13
	v_fmac_f32_e32 v145, v9, v12
	v_fma_f32 v12, v8, v12, v113
	v_fma_f32 v13, v8, v13, v145
	v_fmac_f32_e32 v114, v10, v13
	v_fmac_f32_e32 v146, v9, v12
	v_fma_f32 v12, v8, v12, v114
	v_fma_f32 v13, v8, v13, v146
	v_fmac_f32_e32 v115, v10, v13
	v_fmac_f32_e32 v147, v9, v12
	v_fma_f32 v12, v8, v12, v115
	v_fma_f32 v13, v8, v13, v147
	v_fmac_f32_e32 v128, v10, v13
	v_fmac_f32_e32 v160, v9, v12
	v_fma_f32 v12, v8, v12, v128
	v_fma_f32 v13, v8, v13, v160
	v_fmac_f32_e32 v129, v10, v13
	v_fmac_f32_e32 v161, v9, v12
	v_fma_f32 v12, v8, v12, v129
	v_fma_f32 v13, v8, v13, v161
	v_fmac_f32_e32 v130, v10, v13
	v_fmac_f32_e32 v162, v9, v12
	v_fma_f32 v12, v8, v12, v130
	v_fma_f32 v13, v8, v13, v162
	v_fmac_f32_e32 v131, v10, v13
	v_fmac_f32_e32 v163, v9, v12
	v_fma_f32 v12, v8, v12, v131
	v_fma_f32 v13, v8, v13, v163
	v_fmac_f32_e32 v116, v10, v13
	v_fmac_f32_e32 v148, v9, v12
	v_fma_f32 v12, v8, v12, v116
	v_fma_f32 v13, v8, v13, v148
	v_fmac_f32_e32 v117, v10, v13
	v_fmac_f32_e32 v149, v9, v12
	v_fma_f32 v12, v8, v12, v117
	v_fma_f32 v13, v8, v13, v149
	v_fmac_f32_e32 v118, v10, v13
	v_fmac_f32_e32 v150, v9, v12
	v_fma_f32 v12, v8, v12, v118
	v_fma_f32 v13, v8, v13, v150
	v_fmac_f32_e32 v119, v10, v13
	v_fmac_f32_e32 v151, v9, v12
	v_fma_f32 v12, v8, v12, v119
	v_fma_f32 v13, v8, v13, v151
	v_fmac_f32_e32 v132, v10, v13
	v_fmac_f32_e32 v164, v9, v12
	v_fma_f32 v12, v8, v12, v132
	v_fma_f32 v13, v8, v13, v164
	v_fmac_f32_e32 v133, v10, v13
	v_fmac_f32_e32 v165, v9, v12
	v_fma_f32 v12, v8, v12, v133
	v_fma_f32 v13, v8, v13, v165
	v_fmac_f32_e32 v134, v10, v13
	v_fmac_f32_e32 v166, v9, v12
	v_fma_f32 v12, v8, v12, v134
	v_fma_f32 v13, v8, v13, v166
	v_fmac_f32_e32 v135, v10, v13
	v_fmac_f32_e32 v167, v9, v12
	v_fma_f32 v12, v8, v12, v135
	v_fma_f32 v13, v8, v13, v167
	v_fmac_f32_e32 v120, v10, v13
	v_fmac_f32_e32 v152, v9, v12
	v_fma_f32 v12, v8, v12, v120
	v_fma_f32 v13, v8, v13, v152
	v_fmac_f32_e32 v121, v10, v13
	v_fmac_f32_e32 v153, v9, v12
	v_fma_f32 v12, v8, v12, v121
	v_fma_f32 v13, v8, v13, v153
	v_fmac_f32_e32 v122, v10, v13
	v_fmac_f32_e32 v154, v9, v12
	v_fma_f32 v12, v8, v12, v122
	v_fma_f32 v13, v8, v13, v154
	v_fmac_f32_e32 v123, v10, v13
	v_fmac_f32_e32 v155, v9, v12
	v_fma_f32 v12, v8, v12, v123
	v_fma_f32 v13, v8, v13, v155
	v_fmac_f32_e32 v136, v10, v13
	v_fmac_f32_e32 v168, v9, v12
	v_fma_f32 v12, v8, v12, v136
	v_fma_f32 v13, v8, v13, v168
	v_fmac_f32_e32 v137, v10, v13
	v_fmac_f32_e32 v169, v9, v12
	v_fma_f32 v12, v8, v12, v137
	v_fma_f32 v13, v8, v13, v169
	v_fmac_f32_e32 v138, v10, v13
	v_fmac_f32_e32 v170, v9, v12
	v_fma_f32 v12, v8, v12, v138
	v_fma_f32 v13, v8, v13, v170
	v_fmac_f32_e32 v139, v10, v13
	v_fmac_f32_e32 v171, v9, v12
	v_fma_f32 v12, v8, v12, v139
	v_fma_f32 v13, v8, v13, v171
	v_fmac_f32_e32 v124, v10, v13
	v_fmac_f32_e32 v156, v9, v12
	v_fma_f32 v12, v8, v12, v124
	v_fma_f32 v13, v8, v13, v156
	v_fmac_f32_e32 v125, v10, v13
	v_fmac_f32_e32 v157, v9, v12
	v_fma_f32 v12, v8, v12, v125
	v_fma_f32 v13, v8, v13, v157
	v_fmac_f32_e32 v126, v10, v13
	v_fmac_f32_e32 v158, v9, v12
	v_fma_f32 v12, v8, v12, v126
	v_fma_f32 v13, v8, v13, v158
	v_fmac_f32_e32 v127, v10, v13
	v_fmac_f32_e32 v159, v9, v12
	v_fma_f32 v12, v8, v12, v127
	v_fma_f32 v13, v8, v13, v159
	v_fmac_f32_e32 v140, v10, v13
	v_fmac_f32_e32 v172, v9, v12
	v_fma_f32 v12, v8, v12, v140
	v_fma_f32 v13, v8, v13, v172
	v_fmac_f32_e32 v141, v10, v13
	v_fmac_f32_e32 v173, v9, v12
	v_fma_f32 v12, v8, v12, v141
	v_fma_f32 v13, v8, v13, v173
	v_fmac_f32_e32 v142, v10, v13
	v_fmac_f32_e32 v174, v9, v12
	v_fma_f32 v12, v8, v12, v142
	v_fma_f32 v13, v8, v13, v174
	v_fmac_f32_e32 v143, v10, v13
	v_fmac_f32_e32 v175, v9, v12
	v_fma_f32 v12, v8, v12, v143
	v_fma_f32 v13, v8, v13, v175
	s_waitcnt vmcnt(6)
; #define LDS_WAIT() asm volatile("s_waitcnt lgkmcnt(0)" ::: "memory")
; __device__ __forceinline__ void p5_phase(Frame& F) {
;     ...
;     for (int it = F.gw; it < NB * NCH * NGRP; it += F.ngw) {
;         bf16x8 afr[4];
; #pragma unroll
;         for (int sub = 0; sub < 4; ++sub) afr[sub] = nfr[sub];
;         if (it + F.ngw < NB * NCH * NGRP) { const int bc = (it + F.ngw) >> 7, r0 = (bc / NCH) * SEQ + (bc % NCH) * TCH;
; #pragma unroll
;             for (int sub = 0; sub < 4; ++sub) nfr[sub] = ssm_load_afrag(U, r0 + 16 * sub, g, F.lane); }
;         float sr = 0.f, si = 0.f;
; #pragma unroll
;         for (int sub = 0; sub < 4; ++sub) {
;             ssm_bu16(afr[sub], bf, bubuf, F.lane);
; #pragma unroll
;             for (int tt = 0; tt < 16; ++tt) { const float bur = bubuf[tt * BUP + F.lane], bui = bubuf[tt * BUP + 64 + F.lane];
;                 const float nr = fmaf(ab.x, sr, fmaf(-ab.y, si, bur)), ni = fmaf(ab.x, si, fmaf(ab.y, sr, bui)); sr = nr; si = ni; }
;             LDS_WAIT(); asm volatile("" ::: "memory");
;         }
;         ((f32x2*)(F.ws + WS_E))[(size_t)it * NST + F.lane] = (f32x2){sr, si};
	v_mfma_f32_32x32x16_bf16 v[112:127], v[96:99], v[48:51], 0
	v_mfma_f32_32x32x16_bf16 v[128:143], v[96:99], v[52:55], 0
	v_mfma_f32_32x32x16_bf16 v[144:159], v[96:99], v[56:59], 0
	v_mfma_f32_32x32x16_bf16 v[160:175], v[96:99], v[60:63], 0
	v_mfma_f32_32x32x16_bf16 v[112:127], v[96:99], v[64:67], v[112:127]
	v_mfma_f32_32x32x16_bf16 v[128:143], v[96:99], v[68:71], v[128:143]
	v_mfma_f32_32x32x16_bf16 v[144:159], v[96:99], v[72:75], v[144:159]
	v_mfma_f32_32x32x16_bf16 v[160:175], v[96:99], v[76:79], v[160:175]
	s_nop 3
	v_permlane32_swap_b32_e32 v16, v32
	v_permlane32_swap_b32_e32 v200, v216
	v_permlane32_swap_b32_e32 v17, v33
	v_permlane32_swap_b32_e32 v201, v217
	v_permlane32_swap_b32_e32 v18, v34
	v_permlane32_swap_b32_e32 v202, v218
	v_permlane32_swap_b32_e32 v19, v35
	v_permlane32_swap_b32_e32 v203, v219
	v_permlane32_swap_b32_e32 v20, v36
	v_permlane32_swap_b32_e32 v204, v220
	v_permlane32_swap_b32_e32 v21, v37
	v_permlane32_swap_b32_e32 v205, v221
	v_permlane32_swap_b32_e32 v22, v38
	v_permlane32_swap_b32_e32 v206, v222
	v_permlane32_swap_b32_e32 v23, v39
	v_permlane32_swap_b32_e32 v207, v223
	v_permlane32_swap_b32_e32 v24, v40
	v_permlane32_swap_b32_e32 v208, v224
	v_permlane32_swap_b32_e32 v25, v41
	v_permlane32_swap_b32_e32 v209, v225
	v_permlane32_swap_b32_e32 v26, v42
	v_permlane32_swap_b32_e32 v210, v226
	v_permlane32_swap_b32_e32 v27, v43
	v_permlane32_swap_b32_e32 v211, v227
	v_permlane32_swap_b32_e32 v28, v44
	v_permlane32_swap_b32_e32 v212, v228
	v_permlane32_swap_b32_e32 v29, v45
	v_permlane32_swap_b32_e32 v213, v229
	v_permlane32_swap_b32_e32 v30, v46
	v_permlane32_swap_b32_e32 v214, v230
	v_permlane32_swap_b32_e32 v31, v47
	v_permlane32_swap_b32_e32 v215, v231
	v_fmac_f32_e32 v16, v10, v13
	v_fmac_f32_e32 v200, v9, v12
	v_fma_f32 v12, v8, v12, v16
	v_fma_f32 v13, v8, v13, v200
	v_fmac_f32_e32 v17, v10, v13
	v_fmac_f32_e32 v201, v9, v12
	v_fma_f32 v12, v8, v12, v17
	v_fma_f32 v13, v8, v13, v201
	v_fmac_f32_e32 v18, v10, v13
	v_fmac_f32_e32 v202, v9, v12
	v_fma_f32 v12, v8, v12, v18
	v_fma_f32 v13, v8, v13, v202
	v_fmac_f32_e32 v19, v10, v13
	v_fmac_f32_e32 v203, v9, v12
	v_fma_f32 v12, v8, v12, v19
	v_fma_f32 v13, v8, v13, v203
	v_fmac_f32_e32 v32, v10, v13
	v_fmac_f32_e32 v216, v9, v12
	v_fma_f32 v12, v8, v12, v32
	v_fma_f32 v13, v8, v13, v216
	v_fmac_f32_e32 v33, v10, v13
	v_fmac_f32_e32 v217, v9, v12
	v_fma_f32 v12, v8, v12, v33
	v_fma_f32 v13, v8, v13, v217
	v_fmac_f32_e32 v34, v10, v13
	v_fmac_f32_e32 v218, v9, v12
	v_fma_f32 v12, v8, v12, v34
	v_fma_f32 v13, v8, v13, v218
	v_fmac_f32_e32 v35, v10, v13
	v_fmac_f32_e32 v219, v9, v12
	v_fma_f32 v12, v8, v12, v35
	v_fma_f32 v13, v8, v13, v219
	v_fmac_f32_e32 v20, v10, v13
	v_fmac_f32_e32 v204, v9, v12
	v_fma_f32 v12, v8, v12, v20
	v_fma_f32 v13, v8, v13, v204
	v_fmac_f32_e32 v21, v10, v13
	v_fmac_f32_e32 v205, v9, v12
	v_fma_f32 v12, v8, v12, v21
	v_fma_f32 v13, v8, v13, v205
	v_fmac_f32_e32 v22, v10, v13
	v_fmac_f32_e32 v206, v9, v12
	v_fma_f32 v12, v8, v12, v22
	v_fma_f32 v13, v8, v13, v206
	v_fmac_f32_e32 v23, v10, v13
	v_fmac_f32_e32 v207, v9, v12
	v_fma_f32 v12, v8, v12, v23
	v_fma_f32 v13, v8, v13, v207
	v_fmac_f32_e32 v36, v10, v13
	v_fmac_f32_e32 v220, v9, v12
	v_fma_f32 v12, v8, v12, v36
	v_fma_f32 v13, v8, v13, v220
	v_fmac_f32_e32 v37, v10, v13
	v_fmac_f32_e32 v221, v9, v12
	v_fma_f32 v12, v8, v12, v37
	v_fma_f32 v13, v8, v13, v221
	v_fmac_f32_e32 v38, v10, v13
	v_fmac_f32_e32 v222, v9, v12
	v_fma_f32 v12, v8, v12, v38
	v_fma_f32 v13, v8, v13, v222
	v_fmac_f32_e32 v39, v10, v13
	v_fmac_f32_e32 v223, v9, v12
	v_fma_f32 v12, v8, v12, v39
	v_fma_f32 v13, v8, v13, v223
	v_fmac_f32_e32 v24, v10, v13
	v_fmac_f32_e32 v208, v9, v12
	v_fma_f32 v12, v8, v12, v24
	v_fma_f32 v13, v8, v13, v208
	v_fmac_f32_e32 v25, v10, v13
	v_fmac_f32_e32 v209, v9, v12
	v_fma_f32 v12, v8, v12, v25
	v_fma_f32 v13, v8, v13, v209
	v_fmac_f32_e32 v26, v10, v13
	v_fmac_f32_e32 v210, v9, v12
	v_fma_f32 v12, v8, v12, v26
	v_fma_f32 v13, v8, v13, v210
	v_fmac_f32_e32 v27, v10, v13
	v_fmac_f32_e32 v211, v9, v12
	v_fma_f32 v12, v8, v12, v27
	v_fma_f32 v13, v8, v13, v211
	v_fmac_f32_e32 v40, v10, v13
	v_fmac_f32_e32 v224, v9, v12
	v_fma_f32 v12, v8, v12, v40
	v_fma_f32 v13, v8, v13, v224
	v_fmac_f32_e32 v41, v10, v13
	v_fmac_f32_e32 v225, v9, v12
	v_fma_f32 v12, v8, v12, v41
	v_fma_f32 v13, v8, v13, v225
	v_fmac_f32_e32 v42, v10, v13
	v_fmac_f32_e32 v226, v9, v12
	v_fma_f32 v12, v8, v12, v42
	v_fma_f32 v13, v8, v13, v226
	v_fmac_f32_e32 v43, v10, v13
	v_fmac_f32_e32 v227, v9, v12
	v_fma_f32 v12, v8, v12, v43
	v_fma_f32 v13, v8, v13, v227
	v_fmac_f32_e32 v28, v10, v13
	v_fmac_f32_e32 v212, v9, v12
	v_fma_f32 v12, v8, v12, v28
	v_fma_f32 v13, v8, v13, v212
	v_fmac_f32_e32 v29, v10, v13
	v_fmac_f32_e32 v213, v9, v12
	v_fma_f32 v12, v8, v12, v29
	v_fma_f32 v13, v8, v13, v213
	v_fmac_f32_e32 v30, v10, v13
	v_fmac_f32_e32 v214, v9, v12
	v_fma_f32 v12, v8, v12, v30
	v_fma_f32 v13, v8, v13, v214
	v_fmac_f32_e32 v31, v10, v13
	v_fmac_f32_e32 v215, v9, v12
	v_fma_f32 v12, v8, v12, v31
	v_fma_f32 v13, v8, v13, v215
	v_fmac_f32_e32 v44, v10, v13
	v_fmac_f32_e32 v228, v9, v12
	v_fma_f32 v12, v8, v12, v44
	v_fma_f32 v13, v8, v13, v228
	v_fmac_f32_e32 v45, v10, v13
	v_fmac_f32_e32 v229, v9, v12
	v_fma_f32 v12, v8, v12, v45
	v_fma_f32 v13, v8, v13, v229
	v_fmac_f32_e32 v46, v10, v13
	v_fmac_f32_e32 v230, v9, v12
	v_fma_f32 v12, v8, v12, v46
	v_fma_f32 v13, v8, v13, v230
	v_fmac_f32_e32 v47, v10, v13
	v_fmac_f32_e32 v231, v9, v12
	v_fma_f32 v12, v8, v12, v47
	v_fma_f32 v13, v8, v13, v231
	s_nop 0
	global_store_dwordx2 v7, v[12:13], s[48:49]
	s_add_u32 s48, s48, 0x100000
	s_addc_u32 s49, s49, 0
	global_load_dwordx4 v[88:91], v5, s[54:55]
	global_load_dwordx4 v[92:95], v6, s[54:55]
	s_add_u32 s54, s54, 0x400000
	s_addc_u32 s55, s55, 0
	v_mov_b32_e32 v12, 0
	v_mov_b32_e32 v13, 0
	s_waitcnt vmcnt(8)
; #define LDS_WAIT() asm volatile("s_waitcnt lgkmcnt(0)" ::: "memory")
; __device__ __forceinline__ void p5_phase(Frame& F) {
;     ...
;         float sr = 0.f, si = 0.f;
; #pragma unroll
;         for (int sub = 0; sub < 4; ++sub) {
;             ssm_bu16(afr[sub], bf, bubuf, F.lane);
; #pragma unroll
;             for (int tt = 0; tt < 16; ++tt) { const float bur = bubuf[tt * BUP + F.lane], bui = bubuf[tt * BUP + 64 + F.lane];
;                 const float nr = fmaf(ab.x, sr, fmaf(-ab.y, si, bur)), ni = fmaf(ab.x, si, fmaf(ab.y, sr, bui)); sr = nr; si = ni; }
;             LDS_WAIT(); asm volatile("" ::: "memory");
;         }
	v_mfma_f32_32x32x16_bf16 v[16:31], v[100:103], v[48:51], 0
	v_mfma_f32_32x32x16_bf16 v[32:47], v[100:103], v[52:55], 0
	v_mfma_f32_32x32x16_bf16 v[200:215], v[100:103], v[56:59], 0
	v_mfma_f32_32x32x16_bf16 v[216:231], v[100:103], v[60:63], 0
	v_mfma_f32_32x32x16_bf16 v[16:31], v[100:103], v[64:67], v[16:31]
	v_mfma_f32_32x32x16_bf16 v[32:47], v[100:103], v[68:71], v[32:47]
	v_mfma_f32_32x32x16_bf16 v[200:215], v[100:103], v[72:75], v[200:215]
	v_mfma_f32_32x32x16_bf16 v[216:231], v[100:103], v[76:79], v[216:231]
	s_nop 3
	v_permlane32_swap_b32_e32 v112, v128
	v_permlane32_swap_b32_e32 v144, v160
	v_permlane32_swap_b32_e32 v113, v129
	v_permlane32_swap_b32_e32 v145, v161
	v_permlane32_swap_b32_e32 v114, v130
	v_permlane32_swap_b32_e32 v146, v162
	v_permlane32_swap_b32_e32 v115, v131
	v_permlane32_swap_b32_e32 v147, v163
	v_permlane32_swap_b32_e32 v116, v132
	v_permlane32_swap_b32_e32 v148, v164
	v_permlane32_swap_b32_e32 v117, v133
	v_permlane32_swap_b32_e32 v149, v165
	v_permlane32_swap_b32_e32 v118, v134
	v_permlane32_swap_b32_e32 v150, v166
	v_permlane32_swap_b32_e32 v119, v135
	v_permlane32_swap_b32_e32 v151, v167
	v_permlane32_swap_b32_e32 v120, v136
	v_permlane32_swap_b32_e32 v152, v168
	v_permlane32_swap_b32_e32 v121, v137
	v_permlane32_swap_b32_e32 v153, v169
	v_permlane32_swap_b32_e32 v122, v138
	v_permlane32_swap_b32_e32 v154, v170
	v_permlane32_swap_b32_e32 v123, v139
	v_permlane32_swap_b32_e32 v155, v171
	v_permlane32_swap_b32_e32 v124, v140
	v_permlane32_swap_b32_e32 v156, v172
	v_permlane32_swap_b32_e32 v125, v141
	v_permlane32_swap_b32_e32 v157, v173
	v_permlane32_swap_b32_e32 v126, v142
	v_permlane32_swap_b32_e32 v158, v174
	v_permlane32_swap_b32_e32 v127, v143
	v_permlane32_swap_b32_e32 v159, v175
	v_fmac_f32_e32 v112, v10, v13
	v_fmac_f32_e32 v144, v9, v12
	v_fma_f32 v12, v8, v12, v112
	v_fma_f32 v13, v8, v13, v144
	v_fmac_f32_e32 v113, v10, v13
	v_fmac_f32_e32 v145, v9, v12
	v_fma_f32 v12, v8, v12, v113
	v_fma_f32 v13, v8, v13, v145
	v_fmac_f32_e32 v114, v10, v13
	v_fmac_f32_e32 v146, v9, v12
	v_fma_f32 v12, v8, v12, v114
	v_fma_f32 v13, v8, v13, v146
	v_fmac_f32_e32 v115, v10, v13
	v_fmac_f32_e32 v147, v9, v12
	v_fma_f32 v12, v8, v12, v115
	v_fma_f32 v13, v8, v13, v147
	v_fmac_f32_e32 v128, v10, v13
	v_fmac_f32_e32 v160, v9, v12
	v_fma_f32 v12, v8, v12, v128
	v_fma_f32 v13, v8, v13, v160
	v_fmac_f32_e32 v129, v10, v13
	v_fmac_f32_e32 v161, v9, v12
	v_fma_f32 v12, v8, v12, v129
	v_fma_f32 v13, v8, v13, v161
	v_fmac_f32_e32 v130, v10, v13
	v_fmac_f32_e32 v162, v9, v12
	v_fma_f32 v12, v8, v12, v130
	v_fma_f32 v13, v8, v13, v162
	v_fmac_f32_e32 v131, v10, v13
	v_fmac_f32_e32 v163, v9, v12
	v_fma_f32 v12, v8, v12, v131
	v_fma_f32 v13, v8, v13, v163
	v_fmac_f32_e32 v116, v10, v13
	v_fmac_f32_e32 v148, v9, v12
	v_fma_f32 v12, v8, v12, v116
	v_fma_f32 v13, v8, v13, v148
	v_fmac_f32_e32 v117, v10, v13
	v_fmac_f32_e32 v149, v9, v12
	v_fma_f32 v12, v8, v12, v117
	v_fma_f32 v13, v8, v13, v149
	v_fmac_f32_e32 v118, v10, v13
	v_fmac_f32_e32 v150, v9, v12
	v_fma_f32 v12, v8, v12, v118
	v_fma_f32 v13, v8, v13, v150
	v_fmac_f32_e32 v119, v10, v13
	v_fmac_f32_e32 v151, v9, v12
	v_fma_f32 v12, v8, v12, v119
	v_fma_f32 v13, v8, v13, v151
	v_fmac_f32_e32 v132, v10, v13
	v_fmac_f32_e32 v164, v9, v12
	v_fma_f32 v12, v8, v12, v132
	v_fma_f32 v13, v8, v13, v164
	v_fmac_f32_e32 v133, v10, v13
	v_fmac_f32_e32 v165, v9, v12
	v_fma_f32 v12, v8, v12, v133
	v_fma_f32 v13, v8, v13, v165
	v_fmac_f32_e32 v134, v10, v13
	v_fmac_f32_e32 v166, v9, v12
	v_fma_f32 v12, v8, v12, v134
	v_fma_f32 v13, v8, v13, v166
	v_fmac_f32_e32 v135, v10, v13
	v_fmac_f32_e32 v167, v9, v12
	v_fma_f32 v12, v8, v12, v135
	v_fma_f32 v13, v8, v13, v167
	v_fmac_f32_e32 v120, v10, v13
	v_fmac_f32_e32 v152, v9, v12
	v_fma_f32 v12, v8, v12, v120
	v_fma_f32 v13, v8, v13, v152
	v_fmac_f32_e32 v121, v10, v13
	v_fmac_f32_e32 v153, v9, v12
	v_fma_f32 v12, v8, v12, v121
	v_fma_f32 v13, v8, v13, v153
	v_fmac_f32_e32 v122, v10, v13
	v_fmac_f32_e32 v154, v9, v12
	v_fma_f32 v12, v8, v12, v122
	v_fma_f32 v13, v8, v13, v154
	v_fmac_f32_e32 v123, v10, v13
	v_fmac_f32_e32 v155, v9, v12
	v_fma_f32 v12, v8, v12, v123
	v_fma_f32 v13, v8, v13, v155
	v_fmac_f32_e32 v136, v10, v13
	v_fmac_f32_e32 v168, v9, v12
	v_fma_f32 v12, v8, v12, v136
	v_fma_f32 v13, v8, v13, v168
	v_fmac_f32_e32 v137, v10, v13
	v_fmac_f32_e32 v169, v9, v12
	v_fma_f32 v12, v8, v12, v137
	v_fma_f32 v13, v8, v13, v169
	v_fmac_f32_e32 v138, v10, v13
	v_fmac_f32_e32 v170, v9, v12
	v_fma_f32 v12, v8, v12, v138
	v_fma_f32 v13, v8, v13, v170
	v_fmac_f32_e32 v139, v10, v13
	v_fmac_f32_e32 v171, v9, v12
	v_fma_f32 v12, v8, v12, v139
	v_fma_f32 v13, v8, v13, v171
	v_fmac_f32_e32 v124, v10, v13
	v_fmac_f32_e32 v156, v9, v12
	v_fma_f32 v12, v8, v12, v124
	v_fma_f32 v13, v8, v13, v156
	v_fmac_f32_e32 v125, v10, v13
	v_fmac_f32_e32 v157, v9, v12
	v_fma_f32 v12, v8, v12, v125
	v_fma_f32 v13, v8, v13, v157
	v_fmac_f32_e32 v126, v10, v13
	v_fmac_f32_e32 v158, v9, v12
	v_fma_f32 v12, v8, v12, v126
	v_fma_f32 v13, v8, v13, v158
	v_fmac_f32_e32 v127, v10, v13
	v_fmac_f32_e32 v159, v9, v12
	v_fma_f32 v12, v8, v12, v127
	v_fma_f32 v13, v8, v13, v159
	v_fmac_f32_e32 v140, v10, v13
	v_fmac_f32_e32 v172, v9, v12
	v_fma_f32 v12, v8, v12, v140
	v_fma_f32 v13, v8, v13, v172
	v_fmac_f32_e32 v141, v10, v13
	v_fmac_f32_e32 v173, v9, v12
	v_fma_f32 v12, v8, v12, v141
	v_fma_f32 v13, v8, v13, v173
	v_fmac_f32_e32 v142, v10, v13
	v_fmac_f32_e32 v174, v9, v12
	v_fma_f32 v12, v8, v12, v142
	v_fma_f32 v13, v8, v13, v174
	v_fmac_f32_e32 v143, v10, v13
	v_fmac_f32_e32 v175, v9, v12
	v_fma_f32 v12, v8, v12, v143
	v_fma_f32 v13, v8, v13, v175
	s_waitcnt vmcnt(7)
; #define LDS_WAIT() asm volatile("s_waitcnt lgkmcnt(0)" ::: "memory")
; __device__ __forceinline__ void p5_phase(Frame& F) {
;     ...
;     for (int it = F.gw; it < NB * NCH * NGRP; it += F.ngw) {
;         bf16x8 afr[4];
; #pragma unroll
;         for (int sub = 0; sub < 4; ++sub) afr[sub] = nfr[sub];
;         if (it + F.ngw < NB * NCH * NGRP) { const int bc = (it + F.ngw) >> 7, r0 = (bc / NCH) * SEQ + (bc % NCH) * TCH;
; #pragma unroll
;             for (int sub = 0; sub < 4; ++sub) nfr[sub] = ssm_load_afrag(U, r0 + 16 * sub, g, F.lane); }
;         float sr = 0.f, si = 0.f;
; #pragma unroll
;         for (int sub = 0; sub < 4; ++sub) {
;             ssm_bu16(afr[sub], bf, bubuf, F.lane);
; #pragma unroll
;             for (int tt = 0; tt < 16; ++tt) { const float bur = bubuf[tt * BUP + F.lane], bui = bubuf[tt * BUP + 64 + F.lane];
;                 const float nr = fmaf(ab.x, sr, fmaf(-ab.y, si, bur)), ni = fmaf(ab.x, si, fmaf(ab.y, sr, bui)); sr = nr; si = ni; }
;             LDS_WAIT(); asm volatile("" ::: "memory");
;         }
;         ((f32x2*)(F.ws + WS_E))[(size_t)it * NST + F.lane] = (f32x2){sr, si};
	v_mfma_f32_32x32x16_bf16 v[112:127], v[104:107], v[48:51], 0
	v_mfma_f32_32x32x16_bf16 v[128:143], v[104:107], v[52:55], 0
	v_mfma_f32_32x32x16_bf16 v[144:159], v[104:107], v[56:59], 0
	v_mfma_f32_32x32x16_bf16 v[160:175], v[104:107], v[60:63], 0
	v_mfma_f32_32x32x16_bf16 v[112:127], v[104:107], v[64:67], v[112:127]
	v_mfma_f32_32x32x16_bf16 v[128:143], v[104:107], v[68:71], v[128:143]
	v_mfma_f32_32x32x16_bf16 v[144:159], v[104:107], v[72:75], v[144:159]
	v_mfma_f32_32x32x16_bf16 v[160:175], v[104:107], v[76:79], v[160:175]
	s_nop 3
	v_permlane32_swap_b32_e32 v16, v32
	v_permlane32_swap_b32_e32 v200, v216
	v_permlane32_swap_b32_e32 v17, v33
	v_permlane32_swap_b32_e32 v201, v217
	v_permlane32_swap_b32_e32 v18, v34
	v_permlane32_swap_b32_e32 v202, v218
	v_permlane32_swap_b32_e32 v19, v35
	v_permlane32_swap_b32_e32 v203, v219
	v_permlane32_swap_b32_e32 v20, v36
	v_permlane32_swap_b32_e32 v204, v220
	v_permlane32_swap_b32_e32 v21, v37
	v_permlane32_swap_b32_e32 v205, v221
	v_permlane32_swap_b32_e32 v22, v38
	v_permlane32_swap_b32_e32 v206, v222
	v_permlane32_swap_b32_e32 v23, v39
	v_permlane32_swap_b32_e32 v207, v223
	v_permlane32_swap_b32_e32 v24, v40
	v_permlane32_swap_b32_e32 v208, v224
	v_permlane32_swap_b32_e32 v25, v41
	v_permlane32_swap_b32_e32 v209, v225
	v_permlane32_swap_b32_e32 v26, v42
	v_permlane32_swap_b32_e32 v210, v226
	v_permlane32_swap_b32_e32 v27, v43
	v_permlane32_swap_b32_e32 v211, v227
	v_permlane32_swap_b32_e32 v28, v44
	v_permlane32_swap_b32_e32 v212, v228
	v_permlane32_swap_b32_e32 v29, v45
	v_permlane32_swap_b32_e32 v213, v229
	v_permlane32_swap_b32_e32 v30, v46
	v_permlane32_swap_b32_e32 v214, v230
	v_permlane32_swap_b32_e32 v31, v47
	v_permlane32_swap_b32_e32 v215, v231
	v_fmac_f32_e32 v16, v10, v13
	v_fmac_f32_e32 v200, v9, v12
	v_fma_f32 v12, v8, v12, v16
	v_fma_f32 v13, v8, v13, v200
	v_fmac_f32_e32 v17, v10, v13
	v_fmac_f32_e32 v201, v9, v12
	v_fma_f32 v12, v8, v12, v17
	v_fma_f32 v13, v8, v13, v201
	v_fmac_f32_e32 v18, v10, v13
	v_fmac_f32_e32 v202, v9, v12
	v_fma_f32 v12, v8, v12, v18
	v_fma_f32 v13, v8, v13, v202
	v_fmac_f32_e32 v19, v10, v13
	v_fmac_f32_e32 v203, v9, v12
	v_fma_f32 v12, v8, v12, v19
	v_fma_f32 v13, v8, v13, v203
	v_fmac_f32_e32 v32, v10, v13
	v_fmac_f32_e32 v216, v9, v12
	v_fma_f32 v12, v8, v12, v32
	v_fma_f32 v13, v8, v13, v216
	v_fmac_f32_e32 v33, v10, v13
	v_fmac_f32_e32 v217, v9, v12
	v_fma_f32 v12, v8, v12, v33
	v_fma_f32 v13, v8, v13, v217
	v_fmac_f32_e32 v34, v10, v13
	v_fmac_f32_e32 v218, v9, v12
	v_fma_f32 v12, v8, v12, v34
	v_fma_f32 v13, v8, v13, v218
	v_fmac_f32_e32 v35, v10, v13
	v_fmac_f32_e32 v219, v9, v12
	v_fma_f32 v12, v8, v12, v35
	v_fma_f32 v13, v8, v13, v219
	v_fmac_f32_e32 v20, v10, v13
	v_fmac_f32_e32 v204, v9, v12
	v_fma_f32 v12, v8, v12, v20
	v_fma_f32 v13, v8, v13, v204
	v_fmac_f32_e32 v21, v10, v13
	v_fmac_f32_e32 v205, v9, v12
	v_fma_f32 v12, v8, v12, v21
	v_fma_f32 v13, v8, v13, v205
	v_fmac_f32_e32 v22, v10, v13
	v_fmac_f32_e32 v206, v9, v12
	v_fma_f32 v12, v8, v12, v22
	v_fma_f32 v13, v8, v13, v206
	v_fmac_f32_e32 v23, v10, v13
	v_fmac_f32_e32 v207, v9, v12
	v_fma_f32 v12, v8, v12, v23
	v_fma_f32 v13, v8, v13, v207
	v_fmac_f32_e32 v36, v10, v13
	v_fmac_f32_e32 v220, v9, v12
	v_fma_f32 v12, v8, v12, v36
	v_fma_f32 v13, v8, v13, v220
	v_fmac_f32_e32 v37, v10, v13
	v_fmac_f32_e32 v221, v9, v12
	v_fma_f32 v12, v8, v12, v37
	v_fma_f32 v13, v8, v13, v221
	v_fmac_f32_e32 v38, v10, v13
	v_fmac_f32_e32 v222, v9, v12
	v_fma_f32 v12, v8, v12, v38
	v_fma_f32 v13, v8, v13, v222
	v_fmac_f32_e32 v39, v10, v13
	v_fmac_f32_e32 v223, v9, v12
	v_fma_f32 v12, v8, v12, v39
	v_fma_f32 v13, v8, v13, v223
	v_fmac_f32_e32 v24, v10, v13
	v_fmac_f32_e32 v208, v9, v12
	v_fma_f32 v12, v8, v12, v24
	v_fma_f32 v13, v8, v13, v208
	v_fmac_f32_e32 v25, v10, v13
	v_fmac_f32_e32 v209, v9, v12
	v_fma_f32 v12, v8, v12, v25
	v_fma_f32 v13, v8, v13, v209
	v_fmac_f32_e32 v26, v10, v13
	v_fmac_f32_e32 v210, v9, v12
	v_fma_f32 v12, v8, v12, v26
	v_fma_f32 v13, v8, v13, v210
	v_fmac_f32_e32 v27, v10, v13
	v_fmac_f32_e32 v211, v9, v12
	v_fma_f32 v12, v8, v12, v27
	v_fma_f32 v13, v8, v13, v211
	v_fmac_f32_e32 v40, v10, v13
	v_fmac_f32_e32 v224, v9, v12
	v_fma_f32 v12, v8, v12, v40
	v_fma_f32 v13, v8, v13, v224
	v_fmac_f32_e32 v41, v10, v13
	v_fmac_f32_e32 v225, v9, v12
	v_fma_f32 v12, v8, v12, v41
	v_fma_f32 v13, v8, v13, v225
	v_fmac_f32_e32 v42, v10, v13
	v_fmac_f32_e32 v226, v9, v12
	v_fma_f32 v12, v8, v12, v42
	v_fma_f32 v13, v8, v13, v226
	v_fmac_f32_e32 v43, v10, v13
	v_fmac_f32_e32 v227, v9, v12
	v_fma_f32 v12, v8, v12, v43
	v_fma_f32 v13, v8, v13, v227
	v_fmac_f32_e32 v28, v10, v13
	v_fmac_f32_e32 v212, v9, v12
	v_fma_f32 v12, v8, v12, v28
	v_fma_f32 v13, v8, v13, v212
	v_fmac_f32_e32 v29, v10, v13
	v_fmac_f32_e32 v213, v9, v12
	v_fma_f32 v12, v8, v12, v29
	v_fma_f32 v13, v8, v13, v213
	v_fmac_f32_e32 v30, v10, v13
	v_fmac_f32_e32 v214, v9, v12
	v_fma_f32 v12, v8, v12, v30
	v_fma_f32 v13, v8, v13, v214
	v_fmac_f32_e32 v31, v10, v13
	v_fmac_f32_e32 v215, v9, v12
	v_fma_f32 v12, v8, v12, v31
	v_fma_f32 v13, v8, v13, v215
	v_fmac_f32_e32 v44, v10, v13
	v_fmac_f32_e32 v228, v9, v12
	v_fma_f32 v12, v8, v12, v44
	v_fma_f32 v13, v8, v13, v228
	v_fmac_f32_e32 v45, v10, v13
	v_fmac_f32_e32 v229, v9, v12
	v_fma_f32 v12, v8, v12, v45
	v_fma_f32 v13, v8, v13, v229
	v_fmac_f32_e32 v46, v10, v13
	v_fmac_f32_e32 v230, v9, v12
	v_fma_f32 v12, v8, v12, v46
	v_fma_f32 v13, v8, v13, v230
	v_fmac_f32_e32 v47, v10, v13
	v_fmac_f32_e32 v231, v9, v12
	v_fma_f32 v12, v8, v12, v47
	v_fma_f32 v13, v8, v13, v231
	s_nop 0
	global_store_dwordx2 v7, v[12:13], s[48:49]
	s_add_u32 s48, s48, 0x100000
	s_addc_u32 s49, s49, 0
	global_load_dwordx4 v[96:99], v5, s[54:55]
	global_load_dwordx4 v[100:103], v6, s[54:55]
	s_add_u32 s54, s54, 0x400000
	s_addc_u32 s55, s55, 0
	v_mov_b32_e32 v12, 0
	v_mov_b32_e32 v13, 0
	s_waitcnt vmcnt(9)
; #define LDS_WAIT() asm volatile("s_waitcnt lgkmcnt(0)" ::: "memory")
; __device__ __forceinline__ void p5_phase(Frame& F) {
;     ...
;         float sr = 0.f, si = 0.f;
; #pragma unroll
;         for (int sub = 0; sub < 4; ++sub) {
;             ssm_bu16(afr[sub], bf, bubuf, F.lane);
; #pragma unroll
;             for (int tt = 0; tt < 16; ++tt) { const float bur = bubuf[tt * BUP + F.lane], bui = bubuf[tt * BUP + 64 + F.lane];
;                 const float nr = fmaf(ab.x, sr, fmaf(-ab.y, si, bur)), ni = fmaf(ab.x, si, fmaf(ab.y, sr, bui)); sr = nr; si = ni; }
;             LDS_WAIT(); asm volatile("" ::: "memory");
;         }
	v_mfma_f32_32x32x16_bf16 v[16:31], v[108:111], v[48:51], 0
	v_mfma_f32_32x32x16_bf16 v[32:47], v[108:111], v[52:55], 0
	v_mfma_f32_32x32x16_bf16 v[200:215], v[108:111], v[56:59], 0
	v_mfma_f32_32x32x16_bf16 v[216:231], v[108:111], v[60:63], 0
	v_mfma_f32_32x32x16_bf16 v[16:31], v[108:111], v[64:67], v[16:31]
	v_mfma_f32_32x32x16_bf16 v[32:47], v[108:111], v[68:71], v[32:47]
	v_mfma_f32_32x32x16_bf16 v[200:215], v[108:111], v[72:75], v[200:215]
	v_mfma_f32_32x32x16_bf16 v[216:231], v[108:111], v[76:79], v[216:231]
	s_nop 3
	v_permlane32_swap_b32_e32 v112, v128
	v_permlane32_swap_b32_e32 v144, v160
	v_permlane32_swap_b32_e32 v113, v129
	v_permlane32_swap_b32_e32 v145, v161
	v_permlane32_swap_b32_e32 v114, v130
	v_permlane32_swap_b32_e32 v146, v162
	v_permlane32_swap_b32_e32 v115, v131
	v_permlane32_swap_b32_e32 v147, v163
	v_permlane32_swap_b32_e32 v116, v132
	v_permlane32_swap_b32_e32 v148, v164
	v_permlane32_swap_b32_e32 v117, v133
	v_permlane32_swap_b32_e32 v149, v165
	v_permlane32_swap_b32_e32 v118, v134
	v_permlane32_swap_b32_e32 v150, v166
	v_permlane32_swap_b32_e32 v119, v135
	v_permlane32_swap_b32_e32 v151, v167
	v_permlane32_swap_b32_e32 v120, v136
	v_permlane32_swap_b32_e32 v152, v168
	v_permlane32_swap_b32_e32 v121, v137
	v_permlane32_swap_b32_e32 v153, v169
	v_permlane32_swap_b32_e32 v122, v138
	v_permlane32_swap_b32_e32 v154, v170
	v_permlane32_swap_b32_e32 v123, v139
	v_permlane32_swap_b32_e32 v155, v171
	v_permlane32_swap_b32_e32 v124, v140
	v_permlane32_swap_b32_e32 v156, v172
	v_permlane32_swap_b32_e32 v125, v141
	v_permlane32_swap_b32_e32 v157, v173
	v_permlane32_swap_b32_e32 v126, v142
	v_permlane32_swap_b32_e32 v158, v174
	v_permlane32_swap_b32_e32 v127, v143
	v_permlane32_swap_b32_e32 v159, v175
	v_fmac_f32_e32 v112, v10, v13
	v_fmac_f32_e32 v144, v9, v12
	v_fma_f32 v12, v8, v12, v112
	v_fma_f32 v13, v8, v13, v144
	v_fmac_f32_e32 v113, v10, v13
	v_fmac_f32_e32 v145, v9, v12
	v_fma_f32 v12, v8, v12, v113
	v_fma_f32 v13, v8, v13, v145
	v_fmac_f32_e32 v114, v10, v13
	v_fmac_f32_e32 v146, v9, v12
	v_fma_f32 v12, v8, v12, v114
	v_fma_f32 v13, v8, v13, v146
	v_fmac_f32_e32 v115, v10, v13
	v_fmac_f32_e32 v147, v9, v12
	v_fma_f32 v12, v8, v12, v115
	v_fma_f32 v13, v8, v13, v147
	v_fmac_f32_e32 v128, v10, v13
	v_fmac_f32_e32 v160, v9, v12
	v_fma_f32 v12, v8, v12, v128
	v_fma_f32 v13, v8, v13, v160
	v_fmac_f32_e32 v129, v10, v13
	v_fmac_f32_e32 v161, v9, v12
	v_fma_f32 v12, v8, v12, v129
	v_fma_f32 v13, v8, v13, v161
	v_fmac_f32_e32 v130, v10, v13
	v_fmac_f32_e32 v162, v9, v12
	v_fma_f32 v12, v8, v12, v130
	v_fma_f32 v13, v8, v13, v162
	v_fmac_f32_e32 v131, v10, v13
	v_fmac_f32_e32 v163, v9, v12
	v_fma_f32 v12, v8, v12, v131
	v_fma_f32 v13, v8, v13, v163
	v_fmac_f32_e32 v116, v10, v13
	v_fmac_f32_e32 v148, v9, v12
	v_fma_f32 v12, v8, v12, v116
	v_fma_f32 v13, v8, v13, v148
	v_fmac_f32_e32 v117, v10, v13
	v_fmac_f32_e32 v149, v9, v12
	v_fma_f32 v12, v8, v12, v117
	v_fma_f32 v13, v8, v13, v149
	v_fmac_f32_e32 v118, v10, v13
	v_fmac_f32_e32 v150, v9, v12
	v_fma_f32 v12, v8, v12, v118
	v_fma_f32 v13, v8, v13, v150
	v_fmac_f32_e32 v119, v10, v13
	v_fmac_f32_e32 v151, v9, v12
	v_fma_f32 v12, v8, v12, v119
	v_fma_f32 v13, v8, v13, v151
	v_fmac_f32_e32 v132, v10, v13
	v_fmac_f32_e32 v164, v9, v12
	v_fma_f32 v12, v8, v12, v132
	v_fma_f32 v13, v8, v13, v164
	v_fmac_f32_e32 v133, v10, v13
	v_fmac_f32_e32 v165, v9, v12
	v_fma_f32 v12, v8, v12, v133
	v_fma_f32 v13, v8, v13, v165
	v_fmac_f32_e32 v134, v10, v13
	v_fmac_f32_e32 v166, v9, v12
	v_fma_f32 v12, v8, v12, v134
	v_fma_f32 v13, v8, v13, v166
	v_fmac_f32_e32 v135, v10, v13
	v_fmac_f32_e32 v167, v9, v12
	v_fma_f32 v12, v8, v12, v135
	v_fma_f32 v13, v8, v13, v167
	v_fmac_f32_e32 v120, v10, v13
	v_fmac_f32_e32 v152, v9, v12
	v_fma_f32 v12, v8, v12, v120
	v_fma_f32 v13, v8, v13, v152
	v_fmac_f32_e32 v121, v10, v13
	v_fmac_f32_e32 v153, v9, v12
	v_fma_f32 v12, v8, v12, v121
	v_fma_f32 v13, v8, v13, v153
	v_fmac_f32_e32 v122, v10, v13
	v_fmac_f32_e32 v154, v9, v12
	v_fma_f32 v12, v8, v12, v122
	v_fma_f32 v13, v8, v13, v154
	v_fmac_f32_e32 v123, v10, v13
	v_fmac_f32_e32 v155, v9, v12
	v_fma_f32 v12, v8, v12, v123
	v_fma_f32 v13, v8, v13, v155
	v_fmac_f32_e32 v136, v10, v13
	v_fmac_f32_e32 v168, v9, v12
	v_fma_f32 v12, v8, v12, v136
	v_fma_f32 v13, v8, v13, v168
	v_fmac_f32_e32 v137, v10, v13
	v_fmac_f32_e32 v169, v9, v12
	v_fma_f32 v12, v8, v12, v137
	v_fma_f32 v13, v8, v13, v169
	v_fmac_f32_e32 v138, v10, v13
	v_fmac_f32_e32 v170, v9, v12
	v_fma_f32 v12, v8, v12, v138
	v_fma_f32 v13, v8, v13, v170
	v_fmac_f32_e32 v139, v10, v13
	v_fmac_f32_e32 v171, v9, v12
	v_fma_f32 v12, v8, v12, v139
	v_fma_f32 v13, v8, v13, v171
	v_fmac_f32_e32 v124, v10, v13
	v_fmac_f32_e32 v156, v9, v12
	v_fma_f32 v12, v8, v12, v124
	v_fma_f32 v13, v8, v13, v156
	v_fmac_f32_e32 v125, v10, v13
	v_fmac_f32_e32 v157, v9, v12
	v_fma_f32 v12, v8, v12, v125
	v_fma_f32 v13, v8, v13, v157
	v_fmac_f32_e32 v126, v10, v13
	v_fmac_f32_e32 v158, v9, v12
	v_fma_f32 v12, v8, v12, v126
	v_fma_f32 v13, v8, v13, v158
	v_fmac_f32_e32 v127, v10, v13
	v_fmac_f32_e32 v159, v9, v12
	v_fma_f32 v12, v8, v12, v127
	v_fma_f32 v13, v8, v13, v159
	v_fmac_f32_e32 v140, v10, v13
	v_fmac_f32_e32 v172, v9, v12
	v_fma_f32 v12, v8, v12, v140
	v_fma_f32 v13, v8, v13, v172
	v_fmac_f32_e32 v141, v10, v13
	v_fmac_f32_e32 v173, v9, v12
	v_fma_f32 v12, v8, v12, v141
	v_fma_f32 v13, v8, v13, v173
	v_fmac_f32_e32 v142, v10, v13
	v_fmac_f32_e32 v174, v9, v12
	v_fma_f32 v12, v8, v12, v142
	v_fma_f32 v13, v8, v13, v174
	v_fmac_f32_e32 v143, v10, v13
	v_fmac_f32_e32 v175, v9, v12
	v_fma_f32 v12, v8, v12, v143
	v_fma_f32 v13, v8, v13, v175
	s_waitcnt vmcnt(7)
; #define LDS_WAIT() asm volatile("s_waitcnt lgkmcnt(0)" ::: "memory")
; __device__ __forceinline__ void p5_phase(Frame& F) {
;     ...
;     for (int it = F.gw; it < NB * NCH * NGRP; it += F.ngw) {
;         bf16x8 afr[4];
; #pragma unroll
;         for (int sub = 0; sub < 4; ++sub) afr[sub] = nfr[sub];
;         if (it + F.ngw < NB * NCH * NGRP) { const int bc = (it + F.ngw) >> 7, r0 = (bc / NCH) * SEQ + (bc % NCH) * TCH;
; #pragma unroll
;             for (int sub = 0; sub < 4; ++sub) nfr[sub] = ssm_load_afrag(U, r0 + 16 * sub, g, F.lane); }
;         float sr = 0.f, si = 0.f;
; #pragma unroll
;         for (int sub = 0; sub < 4; ++sub) {
;             ssm_bu16(afr[sub], bf, bubuf, F.lane);
; #pragma unroll
;             for (int tt = 0; tt < 16; ++tt) { const float bur = bubuf[tt * BUP + F.lane], bui = bubuf[tt * BUP + 64 + F.lane];
;                 const float nr = fmaf(ab.x, sr, fmaf(-ab.y, si, bur)), ni = fmaf(ab.x, si, fmaf(ab.y, sr, bui)); sr = nr; si = ni; }
;             LDS_WAIT(); asm volatile("" ::: "memory");
;         }
;         ((f32x2*)(F.ws + WS_E))[(size_t)it * NST + F.lane] = (f32x2){sr, si};
	v_mfma_f32_32x32x16_bf16 v[112:127], v[80:83], v[48:51], 0
	v_mfma_f32_32x32x16_bf16 v[128:143], v[80:83], v[52:55], 0
	v_mfma_f32_32x32x16_bf16 v[144:159], v[80:83], v[56:59], 0
	v_mfma_f32_32x32x16_bf16 v[160:175], v[80:83], v[60:63], 0
	v_mfma_f32_32x32x16_bf16 v[112:127], v[80:83], v[64:67], v[112:127]
	v_mfma_f32_32x32x16_bf16 v[128:143], v[80:83], v[68:71], v[128:143]
	v_mfma_f32_32x32x16_bf16 v[144:159], v[80:83], v[72:75], v[144:159]
	v_mfma_f32_32x32x16_bf16 v[160:175], v[80:83], v[76:79], v[160:175]
	s_nop 3
	v_permlane32_swap_b32_e32 v16, v32
	v_permlane32_swap_b32_e32 v200, v216
	v_permlane32_swap_b32_e32 v17, v33
	v_permlane32_swap_b32_e32 v201, v217
	v_permlane32_swap_b32_e32 v18, v34
	v_permlane32_swap_b32_e32 v202, v218
	v_permlane32_swap_b32_e32 v19, v35
	v_permlane32_swap_b32_e32 v203, v219
	v_permlane32_swap_b32_e32 v20, v36
	v_permlane32_swap_b32_e32 v204, v220
	v_permlane32_swap_b32_e32 v21, v37
	v_permlane32_swap_b32_e32 v205, v221
	v_permlane32_swap_b32_e32 v22, v38
	v_permlane32_swap_b32_e32 v206, v222
	v_permlane32_swap_b32_e32 v23, v39
	v_permlane32_swap_b32_e32 v207, v223
	v_permlane32_swap_b32_e32 v24, v40
	v_permlane32_swap_b32_e32 v208, v224
	v_permlane32_swap_b32_e32 v25, v41
	v_permlane32_swap_b32_e32 v209, v225
	v_permlane32_swap_b32_e32 v26, v42
	v_permlane32_swap_b32_e32 v210, v226
	v_permlane32_swap_b32_e32 v27, v43
	v_permlane32_swap_b32_e32 v211, v227
	v_permlane32_swap_b32_e32 v28, v44
	v_permlane32_swap_b32_e32 v212, v228
	v_permlane32_swap_b32_e32 v29, v45
	v_permlane32_swap_b32_e32 v213, v229
	v_permlane32_swap_b32_e32 v30, v46
	v_permlane32_swap_b32_e32 v214, v230
	v_permlane32_swap_b32_e32 v31, v47
	v_permlane32_swap_b32_e32 v215, v231
	v_fmac_f32_e32 v16, v10, v13
	v_fmac_f32_e32 v200, v9, v12
	v_fma_f32 v12, v8, v12, v16
	v_fma_f32 v13, v8, v13, v200
	v_fmac_f32_e32 v17, v10, v13
	v_fmac_f32_e32 v201, v9, v12
	v_fma_f32 v12, v8, v12, v17
	v_fma_f32 v13, v8, v13, v201
	v_fmac_f32_e32 v18, v10, v13
	v_fmac_f32_e32 v202, v9, v12
	v_fma_f32 v12, v8, v12, v18
	v_fma_f32 v13, v8, v13, v202
	v_fmac_f32_e32 v19, v10, v13
	v_fmac_f32_e32 v203, v9, v12
	v_fma_f32 v12, v8, v12, v19
	v_fma_f32 v13, v8, v13, v203
	v_fmac_f32_e32 v32, v10, v13
	v_fmac_f32_e32 v216, v9, v12
	v_fma_f32 v12, v8, v12, v32
	v_fma_f32 v13, v8, v13, v216
	v_fmac_f32_e32 v33, v10, v13
	v_fmac_f32_e32 v217, v9, v12
	v_fma_f32 v12, v8, v12, v33
	v_fma_f32 v13, v8, v13, v217
	v_fmac_f32_e32 v34, v10, v13
	v_fmac_f32_e32 v218, v9, v12
	v_fma_f32 v12, v8, v12, v34
	v_fma_f32 v13, v8, v13, v218
	v_fmac_f32_e32 v35, v10, v13
	v_fmac_f32_e32 v219, v9, v12
	v_fma_f32 v12, v8, v12, v35
	v_fma_f32 v13, v8, v13, v219
	v_fmac_f32_e32 v20, v10, v13
	v_fmac_f32_e32 v204, v9, v12
	v_fma_f32 v12, v8, v12, v20
	v_fma_f32 v13, v8, v13, v204
	v_fmac_f32_e32 v21, v10, v13
	v_fmac_f32_e32 v205, v9, v12
	v_fma_f32 v12, v8, v12, v21
	v_fma_f32 v13, v8, v13, v205
	v_fmac_f32_e32 v22, v10, v13
	v_fmac_f32_e32 v206, v9, v12
	v_fma_f32 v12, v8, v12, v22
	v_fma_f32 v13, v8, v13, v206
	v_fmac_f32_e32 v23, v10, v13
	v_fmac_f32_e32 v207, v9, v12
	v_fma_f32 v12, v8, v12, v23
	v_fma_f32 v13, v8, v13, v207
	v_fmac_f32_e32 v36, v10, v13
	v_fmac_f32_e32 v220, v9, v12
	v_fma_f32 v12, v8, v12, v36
	v_fma_f32 v13, v8, v13, v220
	v_fmac_f32_e32 v37, v10, v13
	v_fmac_f32_e32 v221, v9, v12
	v_fma_f32 v12, v8, v12, v37
	v_fma_f32 v13, v8, v13, v221
	v_fmac_f32_e32 v38, v10, v13
	v_fmac_f32_e32 v222, v9, v12
	v_fma_f32 v12, v8, v12, v38
	v_fma_f32 v13, v8, v13, v222
	v_fmac_f32_e32 v39, v10, v13
	v_fmac_f32_e32 v223, v9, v12
	v_fma_f32 v12, v8, v12, v39
	v_fma_f32 v13, v8, v13, v223
	v_fmac_f32_e32 v24, v10, v13
	v_fmac_f32_e32 v208, v9, v12
	v_fma_f32 v12, v8, v12, v24
	v_fma_f32 v13, v8, v13, v208
	v_fmac_f32_e32 v25, v10, v13
	v_fmac_f32_e32 v209, v9, v12
	v_fma_f32 v12, v8, v12, v25
	v_fma_f32 v13, v8, v13, v209
	v_fmac_f32_e32 v26, v10, v13
	v_fmac_f32_e32 v210, v9, v12
	v_fma_f32 v12, v8, v12, v26
	v_fma_f32 v13, v8, v13, v210
	v_fmac_f32_e32 v27, v10, v13
	v_fmac_f32_e32 v211, v9, v12
	v_fma_f32 v12, v8, v12, v27
	v_fma_f32 v13, v8, v13, v211
	v_fmac_f32_e32 v40, v10, v13
	v_fmac_f32_e32 v224, v9, v12
	v_fma_f32 v12, v8, v12, v40
	v_fma_f32 v13, v8, v13, v224
	v_fmac_f32_e32 v41, v10, v13
	v_fmac_f32_e32 v225, v9, v12
	v_fma_f32 v12, v8, v12, v41
	v_fma_f32 v13, v8, v13, v225
	v_fmac_f32_e32 v42, v10, v13
	v_fmac_f32_e32 v226, v9, v12
	v_fma_f32 v12, v8, v12, v42
	v_fma_f32 v13, v8, v13, v226
	v_fmac_f32_e32 v43, v10, v13
	v_fmac_f32_e32 v227, v9, v12
	v_fma_f32 v12, v8, v12, v43
	v_fma_f32 v13, v8, v13, v227
	v_fmac_f32_e32 v28, v10, v13
	v_fmac_f32_e32 v212, v9, v12
	v_fma_f32 v12, v8, v12, v28
	v_fma_f32 v13, v8, v13, v212
	v_fmac_f32_e32 v29, v10, v13
	v_fmac_f32_e32 v213, v9, v12
	v_fma_f32 v12, v8, v12, v29
	v_fma_f32 v13, v8, v13, v213
	v_fmac_f32_e32 v30, v10, v13
	v_fmac_f32_e32 v214, v9, v12
	v_fma_f32 v12, v8, v12, v30
	v_fma_f32 v13, v8, v13, v214
	v_fmac_f32_e32 v31, v10, v13
	v_fmac_f32_e32 v215, v9, v12
	v_fma_f32 v12, v8, v12, v31
	v_fma_f32 v13, v8, v13, v215
	v_fmac_f32_e32 v44, v10, v13
	v_fmac_f32_e32 v228, v9, v12
	v_fma_f32 v12, v8, v12, v44
	v_fma_f32 v13, v8, v13, v228
	v_fmac_f32_e32 v45, v10, v13
	v_fmac_f32_e32 v229, v9, v12
	v_fma_f32 v12, v8, v12, v45
	v_fma_f32 v13, v8, v13, v229
	v_fmac_f32_e32 v46, v10, v13
	v_fmac_f32_e32 v230, v9, v12
	v_fma_f32 v12, v8, v12, v46
	v_fma_f32 v13, v8, v13, v230
	v_fmac_f32_e32 v47, v10, v13
	v_fmac_f32_e32 v231, v9, v12
	v_fma_f32 v12, v8, v12, v47
	v_fma_f32 v13, v8, v13, v231
	s_nop 0
	global_store_dwordx2 v7, v[12:13], s[48:49]
	s_add_u32 s48, s48, 0x100000
	s_addc_u32 s49, s49, 0
	global_load_dwordx4 v[104:107], v5, s[54:55]
	global_load_dwordx4 v[108:111], v6, s[54:55]
	s_add_u32 s54, s54, 0x400000
	s_addc_u32 s55, s55, 0
	v_mov_b32_e32 v12, 0
	v_mov_b32_e32 v13, 0
	s_waitcnt vmcnt(9)
; #define LDS_WAIT() asm volatile("s_waitcnt lgkmcnt(0)" ::: "memory")
; __device__ __forceinline__ void p5_phase(Frame& F) {
;     ...
;         float sr = 0.f, si = 0.f;
; #pragma unroll
;         for (int sub = 0; sub < 4; ++sub) {
;             ssm_bu16(afr[sub], bf, bubuf, F.lane);
; #pragma unroll
;             for (int tt = 0; tt < 16; ++tt) { const float bur = bubuf[tt * BUP + F.lane], bui = bubuf[tt * BUP + 64 + F.lane];
;                 const float nr = fmaf(ab.x, sr, fmaf(-ab.y, si, bur)), ni = fmaf(ab.x, si, fmaf(ab.y, sr, bui)); sr = nr; si = ni; }
;             LDS_WAIT(); asm volatile("" ::: "memory");
;         }
	v_mfma_f32_32x32x16_bf16 v[16:31], v[84:87], v[48:51], 0
	v_mfma_f32_32x32x16_bf16 v[32:47], v[84:87], v[52:55], 0
	v_mfma_f32_32x32x16_bf16 v[200:215], v[84:87], v[56:59], 0
	v_mfma_f32_32x32x16_bf16 v[216:231], v[84:87], v[60:63], 0
	v_mfma_f32_32x32x16_bf16 v[16:31], v[84:87], v[64:67], v[16:31]
	v_mfma_f32_32x32x16_bf16 v[32:47], v[84:87], v[68:71], v[32:47]
	v_mfma_f32_32x32x16_bf16 v[200:215], v[84:87], v[72:75], v[200:215]
	v_mfma_f32_32x32x16_bf16 v[216:231], v[84:87], v[76:79], v[216:231]
	s_nop 3
	v_permlane32_swap_b32_e32 v112, v128
	v_permlane32_swap_b32_e32 v144, v160
	v_permlane32_swap_b32_e32 v113, v129
	v_permlane32_swap_b32_e32 v145, v161
	v_permlane32_swap_b32_e32 v114, v130
	v_permlane32_swap_b32_e32 v146, v162
	v_permlane32_swap_b32_e32 v115, v131
	v_permlane32_swap_b32_e32 v147, v163
	v_permlane32_swap_b32_e32 v116, v132
	v_permlane32_swap_b32_e32 v148, v164
	v_permlane32_swap_b32_e32 v117, v133
	v_permlane32_swap_b32_e32 v149, v165
	v_permlane32_swap_b32_e32 v118, v134
	v_permlane32_swap_b32_e32 v150, v166
	v_permlane32_swap_b32_e32 v119, v135
	v_permlane32_swap_b32_e32 v151, v167
	v_permlane32_swap_b32_e32 v120, v136
	v_permlane32_swap_b32_e32 v152, v168
	v_permlane32_swap_b32_e32 v121, v137
	v_permlane32_swap_b32_e32 v153, v169
	v_permlane32_swap_b32_e32 v122, v138
	v_permlane32_swap_b32_e32 v154, v170
	v_permlane32_swap_b32_e32 v123, v139
	v_permlane32_swap_b32_e32 v155, v171
	v_permlane32_swap_b32_e32 v124, v140
	v_permlane32_swap_b32_e32 v156, v172
	v_permlane32_swap_b32_e32 v125, v141
	v_permlane32_swap_b32_e32 v157, v173
	v_permlane32_swap_b32_e32 v126, v142
	v_permlane32_swap_b32_e32 v158, v174
	v_permlane32_swap_b32_e32 v127, v143
	v_permlane32_swap_b32_e32 v159, v175
	v_fmac_f32_e32 v112, v10, v13
	v_fmac_f32_e32 v144, v9, v12
	v_fma_f32 v12, v8, v12, v112
	v_fma_f32 v13, v8, v13, v144
	v_fmac_f32_e32 v113, v10, v13
	v_fmac_f32_e32 v145, v9, v12
	v_fma_f32 v12, v8, v12, v113
	v_fma_f32 v13, v8, v13, v145
	v_fmac_f32_e32 v114, v10, v13
	v_fmac_f32_e32 v146, v9, v12
	v_fma_f32 v12, v8, v12, v114
	v_fma_f32 v13, v8, v13, v146
	v_fmac_f32_e32 v115, v10, v13
	v_fmac_f32_e32 v147, v9, v12
	v_fma_f32 v12, v8, v12, v115
	v_fma_f32 v13, v8, v13, v147
	v_fmac_f32_e32 v128, v10, v13
	v_fmac_f32_e32 v160, v9, v12
	v_fma_f32 v12, v8, v12, v128
	v_fma_f32 v13, v8, v13, v160
	v_fmac_f32_e32 v129, v10, v13
	v_fmac_f32_e32 v161, v9, v12
	v_fma_f32 v12, v8, v12, v129
	v_fma_f32 v13, v8, v13, v161
	v_fmac_f32_e32 v130, v10, v13
	v_fmac_f32_e32 v162, v9, v12
	v_fma_f32 v12, v8, v12, v130
	v_fma_f32 v13, v8, v13, v162
	v_fmac_f32_e32 v131, v10, v13
	v_fmac_f32_e32 v163, v9, v12
	v_fma_f32 v12, v8, v12, v131
	v_fma_f32 v13, v8, v13, v163
	v_fmac_f32_e32 v116, v10, v13
	v_fmac_f32_e32 v148, v9, v12
	v_fma_f32 v12, v8, v12, v116
	v_fma_f32 v13, v8, v13, v148
	v_fmac_f32_e32 v117, v10, v13
	v_fmac_f32_e32 v149, v9, v12
	v_fma_f32 v12, v8, v12, v117
	v_fma_f32 v13, v8, v13, v149
	v_fmac_f32_e32 v118, v10, v13
	v_fmac_f32_e32 v150, v9, v12
	v_fma_f32 v12, v8, v12, v118
	v_fma_f32 v13, v8, v13, v150
	v_fmac_f32_e32 v119, v10, v13
	v_fmac_f32_e32 v151, v9, v12
	v_fma_f32 v12, v8, v12, v119
	v_fma_f32 v13, v8, v13, v151
	v_fmac_f32_e32 v132, v10, v13
	v_fmac_f32_e32 v164, v9, v12
	v_fma_f32 v12, v8, v12, v132
	v_fma_f32 v13, v8, v13, v164
	v_fmac_f32_e32 v133, v10, v13
	v_fmac_f32_e32 v165, v9, v12
	v_fma_f32 v12, v8, v12, v133
	v_fma_f32 v13, v8, v13, v165
	v_fmac_f32_e32 v134, v10, v13
	v_fmac_f32_e32 v166, v9, v12
	v_fma_f32 v12, v8, v12, v134
	v_fma_f32 v13, v8, v13, v166
	v_fmac_f32_e32 v135, v10, v13
	v_fmac_f32_e32 v167, v9, v12
	v_fma_f32 v12, v8, v12, v135
	v_fma_f32 v13, v8, v13, v167
	v_fmac_f32_e32 v120, v10, v13
	v_fmac_f32_e32 v152, v9, v12
	v_fma_f32 v12, v8, v12, v120
	v_fma_f32 v13, v8, v13, v152
	v_fmac_f32_e32 v121, v10, v13
	v_fmac_f32_e32 v153, v9, v12
	v_fma_f32 v12, v8, v12, v121
	v_fma_f32 v13, v8, v13, v153
	v_fmac_f32_e32 v122, v10, v13
	v_fmac_f32_e32 v154, v9, v12
	v_fma_f32 v12, v8, v12, v122
	v_fma_f32 v13, v8, v13, v154
	v_fmac_f32_e32 v123, v10, v13
	v_fmac_f32_e32 v155, v9, v12
	v_fma_f32 v12, v8, v12, v123
	v_fma_f32 v13, v8, v13, v155
	v_fmac_f32_e32 v136, v10, v13
	v_fmac_f32_e32 v168, v9, v12
	v_fma_f32 v12, v8, v12, v136
	v_fma_f32 v13, v8, v13, v168
	v_fmac_f32_e32 v137, v10, v13
	v_fmac_f32_e32 v169, v9, v12
	v_fma_f32 v12, v8, v12, v137
	v_fma_f32 v13, v8, v13, v169
	v_fmac_f32_e32 v138, v10, v13
	v_fmac_f32_e32 v170, v9, v12
	v_fma_f32 v12, v8, v12, v138
	v_fma_f32 v13, v8, v13, v170
	v_fmac_f32_e32 v139, v10, v13
	v_fmac_f32_e32 v171, v9, v12
	v_fma_f32 v12, v8, v12, v139
	v_fma_f32 v13, v8, v13, v171
	v_fmac_f32_e32 v124, v10, v13
	v_fmac_f32_e32 v156, v9, v12
	v_fma_f32 v12, v8, v12, v124
	v_fma_f32 v13, v8, v13, v156
	v_fmac_f32_e32 v125, v10, v13
	v_fmac_f32_e32 v157, v9, v12
	v_fma_f32 v12, v8, v12, v125
	v_fma_f32 v13, v8, v13, v157
	v_fmac_f32_e32 v126, v10, v13
	v_fmac_f32_e32 v158, v9, v12
	v_fma_f32 v12, v8, v12, v126
	v_fma_f32 v13, v8, v13, v158
	v_fmac_f32_e32 v127, v10, v13
	v_fmac_f32_e32 v159, v9, v12
	v_fma_f32 v12, v8, v12, v127
	v_fma_f32 v13, v8, v13, v159
	v_fmac_f32_e32 v140, v10, v13
	v_fmac_f32_e32 v172, v9, v12
	v_fma_f32 v12, v8, v12, v140
	v_fma_f32 v13, v8, v13, v172
	v_fmac_f32_e32 v141, v10, v13
	v_fmac_f32_e32 v173, v9, v12
	v_fma_f32 v12, v8, v12, v141
	v_fma_f32 v13, v8, v13, v173
	v_fmac_f32_e32 v142, v10, v13
	v_fmac_f32_e32 v174, v9, v12
	v_fma_f32 v12, v8, v12, v142
	v_fma_f32 v13, v8, v13, v174
	v_fmac_f32_e32 v143, v10, v13
	v_fmac_f32_e32 v175, v9, v12
	v_fma_f32 v12, v8, v12, v143
	v_fma_f32 v13, v8, v13, v175
	s_waitcnt vmcnt(7)
; #define LDS_WAIT() asm volatile("s_waitcnt lgkmcnt(0)" ::: "memory")
; __device__ __forceinline__ void p5_phase(Frame& F) {
;     ...
;     for (int it = F.gw; it < NB * NCH * NGRP; it += F.ngw) {
;         bf16x8 afr[4];
; #pragma unroll
;         for (int sub = 0; sub < 4; ++sub) afr[sub] = nfr[sub];
;         if (it + F.ngw < NB * NCH * NGRP) { const int bc = (it + F.ngw) >> 7, r0 = (bc / NCH) * SEQ + (bc % NCH) * TCH;
; #pragma unroll
;             for (int sub = 0; sub < 4; ++sub) nfr[sub] = ssm_load_afrag(U, r0 + 16 * sub, g, F.lane); }
;         float sr = 0.f, si = 0.f;
; #pragma unroll
;         for (int sub = 0; sub < 4; ++sub) {
;             ssm_bu16(afr[sub], bf, bubuf, F.lane);
; #pragma unroll
;             for (int tt = 0; tt < 16; ++tt) { const float bur = bubuf[tt * BUP + F.lane], bui = bubuf[tt * BUP + 64 + F.lane];
;                 const float nr = fmaf(ab.x, sr, fmaf(-ab.y, si, bur)), ni = fmaf(ab.x, si, fmaf(ab.y, sr, bui)); sr = nr; si = ni; }
;             LDS_WAIT(); asm volatile("" ::: "memory");
;         }
;         ((f32x2*)(F.ws + WS_E))[(size_t)it * NST + F.lane] = (f32x2){sr, si};
	v_mfma_f32_32x32x16_bf16 v[112:127], v[88:91], v[48:51], 0
	v_mfma_f32_32x32x16_bf16 v[128:143], v[88:91], v[52:55], 0
	v_mfma_f32_32x32x16_bf16 v[144:159], v[88:91], v[56:59], 0
	v_mfma_f32_32x32x16_bf16 v[160:175], v[88:91], v[60:63], 0
	v_mfma_f32_32x32x16_bf16 v[112:127], v[88:91], v[64:67], v[112:127]
	v_mfma_f32_32x32x16_bf16 v[128:143], v[88:91], v[68:71], v[128:143]
	v_mfma_f32_32x32x16_bf16 v[144:159], v[88:91], v[72:75], v[144:159]
	v_mfma_f32_32x32x16_bf16 v[160:175], v[88:91], v[76:79], v[160:175]
	s_nop 3
	v_permlane32_swap_b32_e32 v16, v32
	v_permlane32_swap_b32_e32 v200, v216
	v_permlane32_swap_b32_e32 v17, v33
	v_permlane32_swap_b32_e32 v201, v217
	v_permlane32_swap_b32_e32 v18, v34
	v_permlane32_swap_b32_e32 v202, v218
	v_permlane32_swap_b32_e32 v19, v35
	v_permlane32_swap_b32_e32 v203, v219
	v_permlane32_swap_b32_e32 v20, v36
	v_permlane32_swap_b32_e32 v204, v220
	v_permlane32_swap_b32_e32 v21, v37
	v_permlane32_swap_b32_e32 v205, v221
	v_permlane32_swap_b32_e32 v22, v38
	v_permlane32_swap_b32_e32 v206, v222
	v_permlane32_swap_b32_e32 v23, v39
	v_permlane32_swap_b32_e32 v207, v223
	v_permlane32_swap_b32_e32 v24, v40
	v_permlane32_swap_b32_e32 v208, v224
	v_permlane32_swap_b32_e32 v25, v41
	v_permlane32_swap_b32_e32 v209, v225
	v_permlane32_swap_b32_e32 v26, v42
	v_permlane32_swap_b32_e32 v210, v226
	v_permlane32_swap_b32_e32 v27, v43
	v_permlane32_swap_b32_e32 v211, v227
	v_permlane32_swap_b32_e32 v28, v44
	v_permlane32_swap_b32_e32 v212, v228
	v_permlane32_swap_b32_e32 v29, v45
	v_permlane32_swap_b32_e32 v213, v229
	v_permlane32_swap_b32_e32 v30, v46
	v_permlane32_swap_b32_e32 v214, v230
	v_permlane32_swap_b32_e32 v31, v47
	v_permlane32_swap_b32_e32 v215, v231
	v_fmac_f32_e32 v16, v10, v13
	v_fmac_f32_e32 v200, v9, v12
	v_fma_f32 v12, v8, v12, v16
	v_fma_f32 v13, v8, v13, v200
	v_fmac_f32_e32 v17, v10, v13
	v_fmac_f32_e32 v201, v9, v12
	v_fma_f32 v12, v8, v12, v17
	v_fma_f32 v13, v8, v13, v201
	v_fmac_f32_e32 v18, v10, v13
	v_fmac_f32_e32 v202, v9, v12
	v_fma_f32 v12, v8, v12, v18
	v_fma_f32 v13, v8, v13, v202
	v_fmac_f32_e32 v19, v10, v13
	v_fmac_f32_e32 v203, v9, v12
	v_fma_f32 v12, v8, v12, v19
	v_fma_f32 v13, v8, v13, v203
	v_fmac_f32_e32 v32, v10, v13
	v_fmac_f32_e32 v216, v9, v12
	v_fma_f32 v12, v8, v12, v32
	v_fma_f32 v13, v8, v13, v216
	v_fmac_f32_e32 v33, v10, v13
	v_fmac_f32_e32 v217, v9, v12
	v_fma_f32 v12, v8, v12, v33
	v_fma_f32 v13, v8, v13, v217
	v_fmac_f32_e32 v34, v10, v13
	v_fmac_f32_e32 v218, v9, v12
	v_fma_f32 v12, v8, v12, v34
	v_fma_f32 v13, v8, v13, v218
	v_fmac_f32_e32 v35, v10, v13
	v_fmac_f32_e32 v219, v9, v12
	v_fma_f32 v12, v8, v12, v35
	v_fma_f32 v13, v8, v13, v219
	v_fmac_f32_e32 v20, v10, v13
	v_fmac_f32_e32 v204, v9, v12
	v_fma_f32 v12, v8, v12, v20
	v_fma_f32 v13, v8, v13, v204
	v_fmac_f32_e32 v21, v10, v13
	v_fmac_f32_e32 v205, v9, v12
	v_fma_f32 v12, v8, v12, v21
	v_fma_f32 v13, v8, v13, v205
	v_fmac_f32_e32 v22, v10, v13
	v_fmac_f32_e32 v206, v9, v12
	v_fma_f32 v12, v8, v12, v22
	v_fma_f32 v13, v8, v13, v206
	v_fmac_f32_e32 v23, v10, v13
	v_fmac_f32_e32 v207, v9, v12
	v_fma_f32 v12, v8, v12, v23
	v_fma_f32 v13, v8, v13, v207
	v_fmac_f32_e32 v36, v10, v13
	v_fmac_f32_e32 v220, v9, v12
	v_fma_f32 v12, v8, v12, v36
	v_fma_f32 v13, v8, v13, v220
	v_fmac_f32_e32 v37, v10, v13
	v_fmac_f32_e32 v221, v9, v12
	v_fma_f32 v12, v8, v12, v37
	v_fma_f32 v13, v8, v13, v221
	v_fmac_f32_e32 v38, v10, v13
	v_fmac_f32_e32 v222, v9, v12
	v_fma_f32 v12, v8, v12, v38
	v_fma_f32 v13, v8, v13, v222
	v_fmac_f32_e32 v39, v10, v13
	v_fmac_f32_e32 v223, v9, v12
	v_fma_f32 v12, v8, v12, v39
	v_fma_f32 v13, v8, v13, v223
	v_fmac_f32_e32 v24, v10, v13
	v_fmac_f32_e32 v208, v9, v12
	v_fma_f32 v12, v8, v12, v24
	v_fma_f32 v13, v8, v13, v208
	v_fmac_f32_e32 v25, v10, v13
	v_fmac_f32_e32 v209, v9, v12
	v_fma_f32 v12, v8, v12, v25
	v_fma_f32 v13, v8, v13, v209
	v_fmac_f32_e32 v26, v10, v13
	v_fmac_f32_e32 v210, v9, v12
	v_fma_f32 v12, v8, v12, v26
	v_fma_f32 v13, v8, v13, v210
	v_fmac_f32_e32 v27, v10, v13
	v_fmac_f32_e32 v211, v9, v12
	v_fma_f32 v12, v8, v12, v27
	v_fma_f32 v13, v8, v13, v211
	v_fmac_f32_e32 v40, v10, v13
	v_fmac_f32_e32 v224, v9, v12
	v_fma_f32 v12, v8, v12, v40
	v_fma_f32 v13, v8, v13, v224
	v_fmac_f32_e32 v41, v10, v13
	v_fmac_f32_e32 v225, v9, v12
	v_fma_f32 v12, v8, v12, v41
	v_fma_f32 v13, v8, v13, v225
	v_fmac_f32_e32 v42, v10, v13
	v_fmac_f32_e32 v226, v9, v12
	v_fma_f32 v12, v8, v12, v42
	v_fma_f32 v13, v8, v13, v226
	v_fmac_f32_e32 v43, v10, v13
	v_fmac_f32_e32 v227, v9, v12
	v_fma_f32 v12, v8, v12, v43
	v_fma_f32 v13, v8, v13, v227
	v_fmac_f32_e32 v28, v10, v13
	v_fmac_f32_e32 v212, v9, v12
	v_fma_f32 v12, v8, v12, v28
	v_fma_f32 v13, v8, v13, v212
	v_fmac_f32_e32 v29, v10, v13
	v_fmac_f32_e32 v213, v9, v12
	v_fma_f32 v12, v8, v12, v29
	v_fma_f32 v13, v8, v13, v213
	v_fmac_f32_e32 v30, v10, v13
	v_fmac_f32_e32 v214, v9, v12
	v_fma_f32 v12, v8, v12, v30
	v_fma_f32 v13, v8, v13, v214
	v_fmac_f32_e32 v31, v10, v13
	v_fmac_f32_e32 v215, v9, v12
	v_fma_f32 v12, v8, v12, v31
	v_fma_f32 v13, v8, v13, v215
	v_fmac_f32_e32 v44, v10, v13
	v_fmac_f32_e32 v228, v9, v12
	v_fma_f32 v12, v8, v12, v44
	v_fma_f32 v13, v8, v13, v228
	v_fmac_f32_e32 v45, v10, v13
	v_fmac_f32_e32 v229, v9, v12
	v_fma_f32 v12, v8, v12, v45
	v_fma_f32 v13, v8, v13, v229
	v_fmac_f32_e32 v46, v10, v13
	v_fmac_f32_e32 v230, v9, v12
	v_fma_f32 v12, v8, v12, v46
	v_fma_f32 v13, v8, v13, v230
	v_fmac_f32_e32 v47, v10, v13
	v_fmac_f32_e32 v231, v9, v12
	v_fma_f32 v12, v8, v12, v47
	v_fma_f32 v13, v8, v13, v231
	s_nop 0
	global_store_dwordx2 v7, v[12:13], s[48:49]
	s_add_u32 s48, s48, 0x100000
	s_addc_u32 s49, s49, 0
	v_mov_b32_e32 v12, 0
	v_mov_b32_e32 v13, 0
	s_waitcnt vmcnt(7)
; #define LDS_WAIT() asm volatile("s_waitcnt lgkmcnt(0)" ::: "memory")
; __device__ __forceinline__ void p5_phase(Frame& F) {
;     ...
;         float sr = 0.f, si = 0.f;
; #pragma unroll
;         for (int sub = 0; sub < 4; ++sub) {
;             ssm_bu16(afr[sub], bf, bubuf, F.lane);
; #pragma unroll
;             for (int tt = 0; tt < 16; ++tt) { const float bur = bubuf[tt * BUP + F.lane], bui = bubuf[tt * BUP + 64 + F.lane];
;                 const float nr = fmaf(ab.x, sr, fmaf(-ab.y, si, bur)), ni = fmaf(ab.x, si, fmaf(ab.y, sr, bui)); sr = nr; si = ni; }
;             LDS_WAIT(); asm volatile("" ::: "memory");
;         }
	v_mfma_f32_32x32x16_bf16 v[16:31], v[92:95], v[48:51], 0
	v_mfma_f32_32x32x16_bf16 v[32:47], v[92:95], v[52:55], 0
	v_mfma_f32_32x32x16_bf16 v[200:215], v[92:95], v[56:59], 0
	v_mfma_f32_32x32x16_bf16 v[216:231], v[92:95], v[60:63], 0
	v_mfma_f32_32x32x16_bf16 v[16:31], v[92:95], v[64:67], v[16:31]
	v_mfma_f32_32x32x16_bf16 v[32:47], v[92:95], v[68:71], v[32:47]
	v_mfma_f32_32x32x16_bf16 v[200:215], v[92:95], v[72:75], v[200:215]
	v_mfma_f32_32x32x16_bf16 v[216:231], v[92:95], v[76:79], v[216:231]
	s_nop 3
	v_permlane32_swap_b32_e32 v112, v128
	v_permlane32_swap_b32_e32 v144, v160
	v_permlane32_swap_b32_e32 v113, v129
	v_permlane32_swap_b32_e32 v145, v161
	v_permlane32_swap_b32_e32 v114, v130
	v_permlane32_swap_b32_e32 v146, v162
	v_permlane32_swap_b32_e32 v115, v131
	v_permlane32_swap_b32_e32 v147, v163
	v_permlane32_swap_b32_e32 v116, v132
	v_permlane32_swap_b32_e32 v148, v164
	v_permlane32_swap_b32_e32 v117, v133
	v_permlane32_swap_b32_e32 v149, v165
	v_permlane32_swap_b32_e32 v118, v134
	v_permlane32_swap_b32_e32 v150, v166
	v_permlane32_swap_b32_e32 v119, v135
	v_permlane32_swap_b32_e32 v151, v167
	v_permlane32_swap_b32_e32 v120, v136
	v_permlane32_swap_b32_e32 v152, v168
	v_permlane32_swap_b32_e32 v121, v137
	v_permlane32_swap_b32_e32 v153, v169
	v_permlane32_swap_b32_e32 v122, v138
	v_permlane32_swap_b32_e32 v154, v170
	v_permlane32_swap_b32_e32 v123, v139
	v_permlane32_swap_b32_e32 v155, v171
	v_permlane32_swap_b32_e32 v124, v140
	v_permlane32_swap_b32_e32 v156, v172
	v_permlane32_swap_b32_e32 v125, v141
	v_permlane32_swap_b32_e32 v157, v173
	v_permlane32_swap_b32_e32 v126, v142
	v_permlane32_swap_b32_e32 v158, v174
	v_permlane32_swap_b32_e32 v127, v143
	v_permlane32_swap_b32_e32 v159, v175
	v_fmac_f32_e32 v112, v10, v13
	v_fmac_f32_e32 v144, v9, v12
	v_fma_f32 v12, v8, v12, v112
	v_fma_f32 v13, v8, v13, v144
	v_fmac_f32_e32 v113, v10, v13
	v_fmac_f32_e32 v145, v9, v12
	v_fma_f32 v12, v8, v12, v113
	v_fma_f32 v13, v8, v13, v145
	v_fmac_f32_e32 v114, v10, v13
	v_fmac_f32_e32 v146, v9, v12
	v_fma_f32 v12, v8, v12, v114
	v_fma_f32 v13, v8, v13, v146
	v_fmac_f32_e32 v115, v10, v13
	v_fmac_f32_e32 v147, v9, v12
	v_fma_f32 v12, v8, v12, v115
	v_fma_f32 v13, v8, v13, v147
	v_fmac_f32_e32 v128, v10, v13
	v_fmac_f32_e32 v160, v9, v12
	v_fma_f32 v12, v8, v12, v128
	v_fma_f32 v13, v8, v13, v160
	v_fmac_f32_e32 v129, v10, v13
	v_fmac_f32_e32 v161, v9, v12
	v_fma_f32 v12, v8, v12, v129
	v_fma_f32 v13, v8, v13, v161
	v_fmac_f32_e32 v130, v10, v13
	v_fmac_f32_e32 v162, v9, v12
	v_fma_f32 v12, v8, v12, v130
	v_fma_f32 v13, v8, v13, v162
	v_fmac_f32_e32 v131, v10, v13
	v_fmac_f32_e32 v163, v9, v12
	v_fma_f32 v12, v8, v12, v131
	v_fma_f32 v13, v8, v13, v163
	v_fmac_f32_e32 v116, v10, v13
	v_fmac_f32_e32 v148, v9, v12
	v_fma_f32 v12, v8, v12, v116
	v_fma_f32 v13, v8, v13, v148
	v_fmac_f32_e32 v117, v10, v13
	v_fmac_f32_e32 v149, v9, v12
	v_fma_f32 v12, v8, v12, v117
	v_fma_f32 v13, v8, v13, v149
	v_fmac_f32_e32 v118, v10, v13
	v_fmac_f32_e32 v150, v9, v12
	v_fma_f32 v12, v8, v12, v118
	v_fma_f32 v13, v8, v13, v150
	v_fmac_f32_e32 v119, v10, v13
	v_fmac_f32_e32 v151, v9, v12
	v_fma_f32 v12, v8, v12, v119
	v_fma_f32 v13, v8, v13, v151
	v_fmac_f32_e32 v132, v10, v13
	v_fmac_f32_e32 v164, v9, v12
	v_fma_f32 v12, v8, v12, v132
	v_fma_f32 v13, v8, v13, v164
	v_fmac_f32_e32 v133, v10, v13
	v_fmac_f32_e32 v165, v9, v12
	v_fma_f32 v12, v8, v12, v133
	v_fma_f32 v13, v8, v13, v165
	v_fmac_f32_e32 v134, v10, v13
	v_fmac_f32_e32 v166, v9, v12
	v_fma_f32 v12, v8, v12, v134
	v_fma_f32 v13, v8, v13, v166
	v_fmac_f32_e32 v135, v10, v13
	v_fmac_f32_e32 v167, v9, v12
	v_fma_f32 v12, v8, v12, v135
	v_fma_f32 v13, v8, v13, v167
	v_fmac_f32_e32 v120, v10, v13
	v_fmac_f32_e32 v152, v9, v12
	v_fma_f32 v12, v8, v12, v120
	v_fma_f32 v13, v8, v13, v152
	v_fmac_f32_e32 v121, v10, v13
	v_fmac_f32_e32 v153, v9, v12
	v_fma_f32 v12, v8, v12, v121
	v_fma_f32 v13, v8, v13, v153
	v_fmac_f32_e32 v122, v10, v13
	v_fmac_f32_e32 v154, v9, v12
	v_fma_f32 v12, v8, v12, v122
	v_fma_f32 v13, v8, v13, v154
	v_fmac_f32_e32 v123, v10, v13
	v_fmac_f32_e32 v155, v9, v12
	v_fma_f32 v12, v8, v12, v123
	v_fma_f32 v13, v8, v13, v155
	v_fmac_f32_e32 v136, v10, v13
	v_fmac_f32_e32 v168, v9, v12
	v_fma_f32 v12, v8, v12, v136
	v_fma_f32 v13, v8, v13, v168
	v_fmac_f32_e32 v137, v10, v13
	v_fmac_f32_e32 v169, v9, v12
	v_fma_f32 v12, v8, v12, v137
	v_fma_f32 v13, v8, v13, v169
	v_fmac_f32_e32 v138, v10, v13
	v_fmac_f32_e32 v170, v9, v12
	v_fma_f32 v12, v8, v12, v138
	v_fma_f32 v13, v8, v13, v170
	v_fmac_f32_e32 v139, v10, v13
	v_fmac_f32_e32 v171, v9, v12
	v_fma_f32 v12, v8, v12, v139
	v_fma_f32 v13, v8, v13, v171
	v_fmac_f32_e32 v124, v10, v13
	v_fmac_f32_e32 v156, v9, v12
	v_fma_f32 v12, v8, v12, v124
	v_fma_f32 v13, v8, v13, v156
	v_fmac_f32_e32 v125, v10, v13
	v_fmac_f32_e32 v157, v9, v12
	v_fma_f32 v12, v8, v12, v125
	v_fma_f32 v13, v8, v13, v157
	v_fmac_f32_e32 v126, v10, v13
	v_fmac_f32_e32 v158, v9, v12
	v_fma_f32 v12, v8, v12, v126
	v_fma_f32 v13, v8, v13, v158
	v_fmac_f32_e32 v127, v10, v13
	v_fmac_f32_e32 v159, v9, v12
	v_fma_f32 v12, v8, v12, v127
	v_fma_f32 v13, v8, v13, v159
	v_fmac_f32_e32 v140, v10, v13
	v_fmac_f32_e32 v172, v9, v12
	v_fma_f32 v12, v8, v12, v140
	v_fma_f32 v13, v8, v13, v172
	v_fmac_f32_e32 v141, v10, v13
	v_fmac_f32_e32 v173, v9, v12
	v_fma_f32 v12, v8, v12, v141
	v_fma_f32 v13, v8, v13, v173
	v_fmac_f32_e32 v142, v10, v13
	v_fmac_f32_e32 v174, v9, v12
	v_fma_f32 v12, v8, v12, v142
	v_fma_f32 v13, v8, v13, v174
	v_fmac_f32_e32 v143, v10, v13
	v_fmac_f32_e32 v175, v9, v12
	v_fma_f32 v12, v8, v12, v143
	v_fma_f32 v13, v8, v13, v175
	s_waitcnt vmcnt(5)
; #define LDS_WAIT() asm volatile("s_waitcnt lgkmcnt(0)" ::: "memory")
; __device__ __forceinline__ void p5_phase(Frame& F) {
;     ...
;     for (int it = F.gw; it < NB * NCH * NGRP; it += F.ngw) {
;         bf16x8 afr[4];
; #pragma unroll
;         for (int sub = 0; sub < 4; ++sub) afr[sub] = nfr[sub];
;         if (it + F.ngw < NB * NCH * NGRP) { const int bc = (it + F.ngw) >> 7, r0 = (bc / NCH) * SEQ + (bc % NCH) * TCH;
; #pragma unroll
;             for (int sub = 0; sub < 4; ++sub) nfr[sub] = ssm_load_afrag(U, r0 + 16 * sub, g, F.lane); }
;         float sr = 0.f, si = 0.f;
; #pragma unroll
;         for (int sub = 0; sub < 4; ++sub) {
;             ssm_bu16(afr[sub], bf, bubuf, F.lane);
; #pragma unroll
;             for (int tt = 0; tt < 16; ++tt) { const float bur = bubuf[tt * BUP + F.lane], bui = bubuf[tt * BUP + 64 + F.lane];
;                 const float nr = fmaf(ab.x, sr, fmaf(-ab.y, si, bur)), ni = fmaf(ab.x, si, fmaf(ab.y, sr, bui)); sr = nr; si = ni; }
;             LDS_WAIT(); asm volatile("" ::: "memory");
;         }
;         ((f32x2*)(F.ws + WS_E))[(size_t)it * NST + F.lane] = (f32x2){sr, si};
	v_mfma_f32_32x32x16_bf16 v[112:127], v[96:99], v[48:51], 0
	v_mfma_f32_32x32x16_bf16 v[128:143], v[96:99], v[52:55], 0
	v_mfma_f32_32x32x16_bf16 v[144:159], v[96:99], v[56:59], 0
	v_mfma_f32_32x32x16_bf16 v[160:175], v[96:99], v[60:63], 0
	v_mfma_f32_32x32x16_bf16 v[112:127], v[96:99], v[64:67], v[112:127]
	v_mfma_f32_32x32x16_bf16 v[128:143], v[96:99], v[68:71], v[128:143]
	v_mfma_f32_32x32x16_bf16 v[144:159], v[96:99], v[72:75], v[144:159]
	v_mfma_f32_32x32x16_bf16 v[160:175], v[96:99], v[76:79], v[160:175]
	s_nop 3
	v_permlane32_swap_b32_e32 v16, v32
	v_permlane32_swap_b32_e32 v200, v216
	v_permlane32_swap_b32_e32 v17, v33
	v_permlane32_swap_b32_e32 v201, v217
	v_permlane32_swap_b32_e32 v18, v34
	v_permlane32_swap_b32_e32 v202, v218
	v_permlane32_swap_b32_e32 v19, v35
	v_permlane32_swap_b32_e32 v203, v219
	v_permlane32_swap_b32_e32 v20, v36
	v_permlane32_swap_b32_e32 v204, v220
	v_permlane32_swap_b32_e32 v21, v37
	v_permlane32_swap_b32_e32 v205, v221
	v_permlane32_swap_b32_e32 v22, v38
	v_permlane32_swap_b32_e32 v206, v222
	v_permlane32_swap_b32_e32 v23, v39
	v_permlane32_swap_b32_e32 v207, v223
	v_permlane32_swap_b32_e32 v24, v40
	v_permlane32_swap_b32_e32 v208, v224
	v_permlane32_swap_b32_e32 v25, v41
	v_permlane32_swap_b32_e32 v209, v225
	v_permlane32_swap_b32_e32 v26, v42
	v_permlane32_swap_b32_e32 v210, v226
	v_permlane32_swap_b32_e32 v27, v43
	v_permlane32_swap_b32_e32 v211, v227
	v_permlane32_swap_b32_e32 v28, v44
	v_permlane32_swap_b32_e32 v212, v228
	v_permlane32_swap_b32_e32 v29, v45
	v_permlane32_swap_b32_e32 v213, v229
	v_permlane32_swap_b32_e32 v30, v46
	v_permlane32_swap_b32_e32 v214, v230
	v_permlane32_swap_b32_e32 v31, v47
	v_permlane32_swap_b32_e32 v215, v231
	v_fmac_f32_e32 v16, v10, v13
	v_fmac_f32_e32 v200, v9, v12
	v_fma_f32 v12, v8, v12, v16
	v_fma_f32 v13, v8, v13, v200
	v_fmac_f32_e32 v17, v10, v13
	v_fmac_f32_e32 v201, v9, v12
	v_fma_f32 v12, v8, v12, v17
	v_fma_f32 v13, v8, v13, v201
	v_fmac_f32_e32 v18, v10, v13
	v_fmac_f32_e32 v202, v9, v12
	v_fma_f32 v12, v8, v12, v18
	v_fma_f32 v13, v8, v13, v202
	v_fmac_f32_e32 v19, v10, v13
	v_fmac_f32_e32 v203, v9, v12
	v_fma_f32 v12, v8, v12, v19
	v_fma_f32 v13, v8, v13, v203
	v_fmac_f32_e32 v32, v10, v13
	v_fmac_f32_e32 v216, v9, v12
	v_fma_f32 v12, v8, v12, v32
	v_fma_f32 v13, v8, v13, v216
	v_fmac_f32_e32 v33, v10, v13
	v_fmac_f32_e32 v217, v9, v12
	v_fma_f32 v12, v8, v12, v33
	v_fma_f32 v13, v8, v13, v217
	v_fmac_f32_e32 v34, v10, v13
	v_fmac_f32_e32 v218, v9, v12
	v_fma_f32 v12, v8, v12, v34
	v_fma_f32 v13, v8, v13, v218
	v_fmac_f32_e32 v35, v10, v13
	v_fmac_f32_e32 v219, v9, v12
	v_fma_f32 v12, v8, v12, v35
	v_fma_f32 v13, v8, v13, v219
	v_fmac_f32_e32 v20, v10, v13
	v_fmac_f32_e32 v204, v9, v12
	v_fma_f32 v12, v8, v12, v20
	v_fma_f32 v13, v8, v13, v204
	v_fmac_f32_e32 v21, v10, v13
	v_fmac_f32_e32 v205, v9, v12
	v_fma_f32 v12, v8, v12, v21
	v_fma_f32 v13, v8, v13, v205
	v_fmac_f32_e32 v22, v10, v13
	v_fmac_f32_e32 v206, v9, v12
	v_fma_f32 v12, v8, v12, v22
	v_fma_f32 v13, v8, v13, v206
	v_fmac_f32_e32 v23, v10, v13
	v_fmac_f32_e32 v207, v9, v12
	v_fma_f32 v12, v8, v12, v23
	v_fma_f32 v13, v8, v13, v207
	v_fmac_f32_e32 v36, v10, v13
	v_fmac_f32_e32 v220, v9, v12
	v_fma_f32 v12, v8, v12, v36
	v_fma_f32 v13, v8, v13, v220
	v_fmac_f32_e32 v37, v10, v13
	v_fmac_f32_e32 v221, v9, v12
	v_fma_f32 v12, v8, v12, v37
	v_fma_f32 v13, v8, v13, v221
	v_fmac_f32_e32 v38, v10, v13
	v_fmac_f32_e32 v222, v9, v12
	v_fma_f32 v12, v8, v12, v38
	v_fma_f32 v13, v8, v13, v222
	v_fmac_f32_e32 v39, v10, v13
	v_fmac_f32_e32 v223, v9, v12
	v_fma_f32 v12, v8, v12, v39
	v_fma_f32 v13, v8, v13, v223
	v_fmac_f32_e32 v24, v10, v13
	v_fmac_f32_e32 v208, v9, v12
	v_fma_f32 v12, v8, v12, v24
	v_fma_f32 v13, v8, v13, v208
	v_fmac_f32_e32 v25, v10, v13
	v_fmac_f32_e32 v209, v9, v12
	v_fma_f32 v12, v8, v12, v25
	v_fma_f32 v13, v8, v13, v209
	v_fmac_f32_e32 v26, v10, v13
	v_fmac_f32_e32 v210, v9, v12
	v_fma_f32 v12, v8, v12, v26
	v_fma_f32 v13, v8, v13, v210
	v_fmac_f32_e32 v27, v10, v13
	v_fmac_f32_e32 v211, v9, v12
	v_fma_f32 v12, v8, v12, v27
	v_fma_f32 v13, v8, v13, v211
	v_fmac_f32_e32 v40, v10, v13
	v_fmac_f32_e32 v224, v9, v12
	v_fma_f32 v12, v8, v12, v40
	v_fma_f32 v13, v8, v13, v224
	v_fmac_f32_e32 v41, v10, v13
	v_fmac_f32_e32 v225, v9, v12
	v_fma_f32 v12, v8, v12, v41
	v_fma_f32 v13, v8, v13, v225
	v_fmac_f32_e32 v42, v10, v13
	v_fmac_f32_e32 v226, v9, v12
	v_fma_f32 v12, v8, v12, v42
	v_fma_f32 v13, v8, v13, v226
	v_fmac_f32_e32 v43, v10, v13
	v_fmac_f32_e32 v227, v9, v12
	v_fma_f32 v12, v8, v12, v43
	v_fma_f32 v13, v8, v13, v227
	v_fmac_f32_e32 v28, v10, v13
	v_fmac_f32_e32 v212, v9, v12
	v_fma_f32 v12, v8, v12, v28
	v_fma_f32 v13, v8, v13, v212
	v_fmac_f32_e32 v29, v10, v13
	v_fmac_f32_e32 v213, v9, v12
	v_fma_f32 v12, v8, v12, v29
	v_fma_f32 v13, v8, v13, v213
	v_fmac_f32_e32 v30, v10, v13
	v_fmac_f32_e32 v214, v9, v12
	v_fma_f32 v12, v8, v12, v30
	v_fma_f32 v13, v8, v13, v214
	v_fmac_f32_e32 v31, v10, v13
	v_fmac_f32_e32 v215, v9, v12
	v_fma_f32 v12, v8, v12, v31
	v_fma_f32 v13, v8, v13, v215
	v_fmac_f32_e32 v44, v10, v13
	v_fmac_f32_e32 v228, v9, v12
	v_fma_f32 v12, v8, v12, v44
	v_fma_f32 v13, v8, v13, v228
	v_fmac_f32_e32 v45, v10, v13
	v_fmac_f32_e32 v229, v9, v12
	v_fma_f32 v12, v8, v12, v45
	v_fma_f32 v13, v8, v13, v229
	v_fmac_f32_e32 v46, v10, v13
	v_fmac_f32_e32 v230, v9, v12
	v_fma_f32 v12, v8, v12, v46
	v_fma_f32 v13, v8, v13, v230
	v_fmac_f32_e32 v47, v10, v13
	v_fmac_f32_e32 v231, v9, v12
	v_fma_f32 v12, v8, v12, v47
	v_fma_f32 v13, v8, v13, v231
	s_nop 0
	global_store_dwordx2 v7, v[12:13], s[48:49]
	s_add_u32 s48, s48, 0x100000
	s_addc_u32 s49, s49, 0
	v_mov_b32_e32 v12, 0
	v_mov_b32_e32 v13, 0
	s_waitcnt vmcnt(5)
; #define LDS_WAIT() asm volatile("s_waitcnt lgkmcnt(0)" ::: "memory")
; __device__ __forceinline__ void p5_phase(Frame& F) {
;     ...
;         float sr = 0.f, si = 0.f;
; #pragma unroll
;         for (int sub = 0; sub < 4; ++sub) {
;             ssm_bu16(afr[sub], bf, bubuf, F.lane);
; #pragma unroll
;             for (int tt = 0; tt < 16; ++tt) { const float bur = bubuf[tt * BUP + F.lane], bui = bubuf[tt * BUP + 64 + F.lane];
;                 const float nr = fmaf(ab.x, sr, fmaf(-ab.y, si, bur)), ni = fmaf(ab.x, si, fmaf(ab.y, sr, bui)); sr = nr; si = ni; }
;             LDS_WAIT(); asm volatile("" ::: "memory");
;         }
	v_mfma_f32_32x32x16_bf16 v[16:31], v[100:103], v[48:51], 0
	v_mfma_f32_32x32x16_bf16 v[32:47], v[100:103], v[52:55], 0
	v_mfma_f32_32x32x16_bf16 v[200:215], v[100:103], v[56:59], 0
	v_mfma_f32_32x32x16_bf16 v[216:231], v[100:103], v[60:63], 0
	v_mfma_f32_32x32x16_bf16 v[16:31], v[100:103], v[64:67], v[16:31]
	v_mfma_f32_32x32x16_bf16 v[32:47], v[100:103], v[68:71], v[32:47]
	v_mfma_f32_32x32x16_bf16 v[200:215], v[100:103], v[72:75], v[200:215]
	v_mfma_f32_32x32x16_bf16 v[216:231], v[100:103], v[76:79], v[216:231]
	s_nop 3
	v_permlane32_swap_b32_e32 v112, v128
	v_permlane32_swap_b32_e32 v144, v160
	v_permlane32_swap_b32_e32 v113, v129
	v_permlane32_swap_b32_e32 v145, v161
	v_permlane32_swap_b32_e32 v114, v130
	v_permlane32_swap_b32_e32 v146, v162
	v_permlane32_swap_b32_e32 v115, v131
	v_permlane32_swap_b32_e32 v147, v163
	v_permlane32_swap_b32_e32 v116, v132
	v_permlane32_swap_b32_e32 v148, v164
	v_permlane32_swap_b32_e32 v117, v133
	v_permlane32_swap_b32_e32 v149, v165
	v_permlane32_swap_b32_e32 v118, v134
	v_permlane32_swap_b32_e32 v150, v166
	v_permlane32_swap_b32_e32 v119, v135
	v_permlane32_swap_b32_e32 v151, v167
	v_permlane32_swap_b32_e32 v120, v136
	v_permlane32_swap_b32_e32 v152, v168
	v_permlane32_swap_b32_e32 v121, v137
	v_permlane32_swap_b32_e32 v153, v169
	v_permlane32_swap_b32_e32 v122, v138
	v_permlane32_swap_b32_e32 v154, v170
	v_permlane32_swap_b32_e32 v123, v139
	v_permlane32_swap_b32_e32 v155, v171
	v_permlane32_swap_b32_e32 v124, v140
	v_permlane32_swap_b32_e32 v156, v172
	v_permlane32_swap_b32_e32 v125, v141
	v_permlane32_swap_b32_e32 v157, v173
	v_permlane32_swap_b32_e32 v126, v142
	v_permlane32_swap_b32_e32 v158, v174
	v_permlane32_swap_b32_e32 v127, v143
	v_permlane32_swap_b32_e32 v159, v175
	v_fmac_f32_e32 v112, v10, v13
	v_fmac_f32_e32 v144, v9, v12
	v_fma_f32 v12, v8, v12, v112
	v_fma_f32 v13, v8, v13, v144
	v_fmac_f32_e32 v113, v10, v13
	v_fmac_f32_e32 v145, v9, v12
	v_fma_f32 v12, v8, v12, v113
	v_fma_f32 v13, v8, v13, v145
	v_fmac_f32_e32 v114, v10, v13
	v_fmac_f32_e32 v146, v9, v12
	v_fma_f32 v12, v8, v12, v114
	v_fma_f32 v13, v8, v13, v146
	v_fmac_f32_e32 v115, v10, v13
	v_fmac_f32_e32 v147, v9, v12
	v_fma_f32 v12, v8, v12, v115
	v_fma_f32 v13, v8, v13, v147
	v_fmac_f32_e32 v128, v10, v13
	v_fmac_f32_e32 v160, v9, v12
	v_fma_f32 v12, v8, v12, v128
	v_fma_f32 v13, v8, v13, v160
	v_fmac_f32_e32 v129, v10, v13
	v_fmac_f32_e32 v161, v9, v12
	v_fma_f32 v12, v8, v12, v129
	v_fma_f32 v13, v8, v13, v161
	v_fmac_f32_e32 v130, v10, v13
	v_fmac_f32_e32 v162, v9, v12
	v_fma_f32 v12, v8, v12, v130
	v_fma_f32 v13, v8, v13, v162
	v_fmac_f32_e32 v131, v10, v13
	v_fmac_f32_e32 v163, v9, v12
	v_fma_f32 v12, v8, v12, v131
	v_fma_f32 v13, v8, v13, v163
	v_fmac_f32_e32 v116, v10, v13
	v_fmac_f32_e32 v148, v9, v12
	v_fma_f32 v12, v8, v12, v116
	v_fma_f32 v13, v8, v13, v148
	v_fmac_f32_e32 v117, v10, v13
	v_fmac_f32_e32 v149, v9, v12
	v_fma_f32 v12, v8, v12, v117
	v_fma_f32 v13, v8, v13, v149
	v_fmac_f32_e32 v118, v10, v13
	v_fmac_f32_e32 v150, v9, v12
	v_fma_f32 v12, v8, v12, v118
	v_fma_f32 v13, v8, v13, v150
	v_fmac_f32_e32 v119, v10, v13
	v_fmac_f32_e32 v151, v9, v12
	v_fma_f32 v12, v8, v12, v119
	v_fma_f32 v13, v8, v13, v151
	v_fmac_f32_e32 v132, v10, v13
	v_fmac_f32_e32 v164, v9, v12
	v_fma_f32 v12, v8, v12, v132
	v_fma_f32 v13, v8, v13, v164
	v_fmac_f32_e32 v133, v10, v13
	v_fmac_f32_e32 v165, v9, v12
	v_fma_f32 v12, v8, v12, v133
	v_fma_f32 v13, v8, v13, v165
	v_fmac_f32_e32 v134, v10, v13
	v_fmac_f32_e32 v166, v9, v12
	v_fma_f32 v12, v8, v12, v134
	v_fma_f32 v13, v8, v13, v166
	v_fmac_f32_e32 v135, v10, v13
	v_fmac_f32_e32 v167, v9, v12
	v_fma_f32 v12, v8, v12, v135
	v_fma_f32 v13, v8, v13, v167
	v_fmac_f32_e32 v120, v10, v13
	v_fmac_f32_e32 v152, v9, v12
	v_fma_f32 v12, v8, v12, v120
	v_fma_f32 v13, v8, v13, v152
	v_fmac_f32_e32 v121, v10, v13
	v_fmac_f32_e32 v153, v9, v12
	v_fma_f32 v12, v8, v12, v121
	v_fma_f32 v13, v8, v13, v153
	v_fmac_f32_e32 v122, v10, v13
	v_fmac_f32_e32 v154, v9, v12
	v_fma_f32 v12, v8, v12, v122
	v_fma_f32 v13, v8, v13, v154
	v_fmac_f32_e32 v123, v10, v13
	v_fmac_f32_e32 v155, v9, v12
	v_fma_f32 v12, v8, v12, v123
	v_fma_f32 v13, v8, v13, v155
	v_fmac_f32_e32 v136, v10, v13
	v_fmac_f32_e32 v168, v9, v12
	v_fma_f32 v12, v8, v12, v136
	v_fma_f32 v13, v8, v13, v168
	v_fmac_f32_e32 v137, v10, v13
	v_fmac_f32_e32 v169, v9, v12
	v_fma_f32 v12, v8, v12, v137
	v_fma_f32 v13, v8, v13, v169
	v_fmac_f32_e32 v138, v10, v13
	v_fmac_f32_e32 v170, v9, v12
	v_fma_f32 v12, v8, v12, v138
	v_fma_f32 v13, v8, v13, v170
	v_fmac_f32_e32 v139, v10, v13
	v_fmac_f32_e32 v171, v9, v12
	v_fma_f32 v12, v8, v12, v139
	v_fma_f32 v13, v8, v13, v171
	v_fmac_f32_e32 v124, v10, v13
	v_fmac_f32_e32 v156, v9, v12
	v_fma_f32 v12, v8, v12, v124
	v_fma_f32 v13, v8, v13, v156
	v_fmac_f32_e32 v125, v10, v13
	v_fmac_f32_e32 v157, v9, v12
	v_fma_f32 v12, v8, v12, v125
	v_fma_f32 v13, v8, v13, v157
	v_fmac_f32_e32 v126, v10, v13
	v_fmac_f32_e32 v158, v9, v12
	v_fma_f32 v12, v8, v12, v126
	v_fma_f32 v13, v8, v13, v158
	v_fmac_f32_e32 v127, v10, v13
	v_fmac_f32_e32 v159, v9, v12
	v_fma_f32 v12, v8, v12, v127
	v_fma_f32 v13, v8, v13, v159
	v_fmac_f32_e32 v140, v10, v13
	v_fmac_f32_e32 v172, v9, v12
	v_fma_f32 v12, v8, v12, v140
	v_fma_f32 v13, v8, v13, v172
	v_fmac_f32_e32 v141, v10, v13
	v_fmac_f32_e32 v173, v9, v12
	v_fma_f32 v12, v8, v12, v141
	v_fma_f32 v13, v8, v13, v173
	v_fmac_f32_e32 v142, v10, v13
	v_fmac_f32_e32 v174, v9, v12
	v_fma_f32 v12, v8, v12, v142
	v_fma_f32 v13, v8, v13, v174
	v_fmac_f32_e32 v143, v10, v13
	v_fmac_f32_e32 v175, v9, v12
	v_fma_f32 v12, v8, v12, v143
	v_fma_f32 v13, v8, v13, v175
	s_waitcnt vmcnt(3)
; #define LDS_WAIT() asm volatile("s_waitcnt lgkmcnt(0)" ::: "memory")
; __device__ __forceinline__ void p5_phase(Frame& F) {
;     ...
;     for (int it = F.gw; it < NB * NCH * NGRP; it += F.ngw) {
;         bf16x8 afr[4];
; #pragma unroll
;         for (int sub = 0; sub < 4; ++sub) afr[sub] = nfr[sub];
;         if (it + F.ngw < NB * NCH * NGRP) { const int bc = (it + F.ngw) >> 7, r0 = (bc / NCH) * SEQ + (bc % NCH) * TCH;
; #pragma unroll
;             for (int sub = 0; sub < 4; ++sub) nfr[sub] = ssm_load_afrag(U, r0 + 16 * sub, g, F.lane); }
;         float sr = 0.f, si = 0.f;
; #pragma unroll
;         for (int sub = 0; sub < 4; ++sub) {
;             ssm_bu16(afr[sub], bf, bubuf, F.lane);
; #pragma unroll
;             for (int tt = 0; tt < 16; ++tt) { const float bur = bubuf[tt * BUP + F.lane], bui = bubuf[tt * BUP + 64 + F.lane];
;                 const float nr = fmaf(ab.x, sr, fmaf(-ab.y, si, bur)), ni = fmaf(ab.x, si, fmaf(ab.y, sr, bui)); sr = nr; si = ni; }
;             LDS_WAIT(); asm volatile("" ::: "memory");
;         }
;         ((f32x2*)(F.ws + WS_E))[(size_t)it * NST + F.lane] = (f32x2){sr, si};
	v_mfma_f32_32x32x16_bf16 v[112:127], v[104:107], v[48:51], 0
	v_mfma_f32_32x32x16_bf16 v[128:143], v[104:107], v[52:55], 0
	v_mfma_f32_32x32x16_bf16 v[144:159], v[104:107], v[56:59], 0
	v_mfma_f32_32x32x16_bf16 v[160:175], v[104:107], v[60:63], 0
	v_mfma_f32_32x32x16_bf16 v[112:127], v[104:107], v[64:67], v[112:127]
	v_mfma_f32_32x32x16_bf16 v[128:143], v[104:107], v[68:71], v[128:143]
	v_mfma_f32_32x32x16_bf16 v[144:159], v[104:107], v[72:75], v[144:159]
	v_mfma_f32_32x32x16_bf16 v[160:175], v[104:107], v[76:79], v[160:175]
	s_nop 3
	v_permlane32_swap_b32_e32 v16, v32
	v_permlane32_swap_b32_e32 v200, v216
	v_permlane32_swap_b32_e32 v17, v33
	v_permlane32_swap_b32_e32 v201, v217
	v_permlane32_swap_b32_e32 v18, v34
	v_permlane32_swap_b32_e32 v202, v218
	v_permlane32_swap_b32_e32 v19, v35
	v_permlane32_swap_b32_e32 v203, v219
	v_permlane32_swap_b32_e32 v20, v36
	v_permlane32_swap_b32_e32 v204, v220
	v_permlane32_swap_b32_e32 v21, v37
	v_permlane32_swap_b32_e32 v205, v221
	v_permlane32_swap_b32_e32 v22, v38
	v_permlane32_swap_b32_e32 v206, v222
	v_permlane32_swap_b32_e32 v23, v39
	v_permlane32_swap_b32_e32 v207, v223
	v_permlane32_swap_b32_e32 v24, v40
	v_permlane32_swap_b32_e32 v208, v224
	v_permlane32_swap_b32_e32 v25, v41
	v_permlane32_swap_b32_e32 v209, v225
	v_permlane32_swap_b32_e32 v26, v42
	v_permlane32_swap_b32_e32 v210, v226
	v_permlane32_swap_b32_e32 v27, v43
	v_permlane32_swap_b32_e32 v211, v227
	v_permlane32_swap_b32_e32 v28, v44
	v_permlane32_swap_b32_e32 v212, v228
	v_permlane32_swap_b32_e32 v29, v45
	v_permlane32_swap_b32_e32 v213, v229
	v_permlane32_swap_b32_e32 v30, v46
	v_permlane32_swap_b32_e32 v214, v230
	v_permlane32_swap_b32_e32 v31, v47
	v_permlane32_swap_b32_e32 v215, v231
	v_fmac_f32_e32 v16, v10, v13
	v_fmac_f32_e32 v200, v9, v12
	v_fma_f32 v12, v8, v12, v16
	v_fma_f32 v13, v8, v13, v200
	v_fmac_f32_e32 v17, v10, v13
	v_fmac_f32_e32 v201, v9, v12
	v_fma_f32 v12, v8, v12, v17
	v_fma_f32 v13, v8, v13, v201
	v_fmac_f32_e32 v18, v10, v13
	v_fmac_f32_e32 v202, v9, v12
	v_fma_f32 v12, v8, v12, v18
	v_fma_f32 v13, v8, v13, v202
	v_fmac_f32_e32 v19, v10, v13
	v_fmac_f32_e32 v203, v9, v12
	v_fma_f32 v12, v8, v12, v19
	v_fma_f32 v13, v8, v13, v203
	v_fmac_f32_e32 v32, v10, v13
	v_fmac_f32_e32 v216, v9, v12
	v_fma_f32 v12, v8, v12, v32
	v_fma_f32 v13, v8, v13, v216
	v_fmac_f32_e32 v33, v10, v13
	v_fmac_f32_e32 v217, v9, v12
	v_fma_f32 v12, v8, v12, v33
	v_fma_f32 v13, v8, v13, v217
	v_fmac_f32_e32 v34, v10, v13
	v_fmac_f32_e32 v218, v9, v12
	v_fma_f32 v12, v8, v12, v34
	v_fma_f32 v13, v8, v13, v218
	v_fmac_f32_e32 v35, v10, v13
	v_fmac_f32_e32 v219, v9, v12
	v_fma_f32 v12, v8, v12, v35
	v_fma_f32 v13, v8, v13, v219
	v_fmac_f32_e32 v20, v10, v13
	v_fmac_f32_e32 v204, v9, v12
	v_fma_f32 v12, v8, v12, v20
	v_fma_f32 v13, v8, v13, v204
	v_fmac_f32_e32 v21, v10, v13
	v_fmac_f32_e32 v205, v9, v12
	v_fma_f32 v12, v8, v12, v21
	v_fma_f32 v13, v8, v13, v205
	v_fmac_f32_e32 v22, v10, v13
	v_fmac_f32_e32 v206, v9, v12
	v_fma_f32 v12, v8, v12, v22
	v_fma_f32 v13, v8, v13, v206
	v_fmac_f32_e32 v23, v10, v13
	v_fmac_f32_e32 v207, v9, v12
	v_fma_f32 v12, v8, v12, v23
	v_fma_f32 v13, v8, v13, v207
	v_fmac_f32_e32 v36, v10, v13
	v_fmac_f32_e32 v220, v9, v12
	v_fma_f32 v12, v8, v12, v36
	v_fma_f32 v13, v8, v13, v220
	v_fmac_f32_e32 v37, v10, v13
	v_fmac_f32_e32 v221, v9, v12
	v_fma_f32 v12, v8, v12, v37
	v_fma_f32 v13, v8, v13, v221
	v_fmac_f32_e32 v38, v10, v13
	v_fmac_f32_e32 v222, v9, v12
	v_fma_f32 v12, v8, v12, v38
	v_fma_f32 v13, v8, v13, v222
	v_fmac_f32_e32 v39, v10, v13
	v_fmac_f32_e32 v223, v9, v12
	v_fma_f32 v12, v8, v12, v39
	v_fma_f32 v13, v8, v13, v223
	v_fmac_f32_e32 v24, v10, v13
	v_fmac_f32_e32 v208, v9, v12
	v_fma_f32 v12, v8, v12, v24
	v_fma_f32 v13, v8, v13, v208
	v_fmac_f32_e32 v25, v10, v13
	v_fmac_f32_e32 v209, v9, v12
	v_fma_f32 v12, v8, v12, v25
	v_fma_f32 v13, v8, v13, v209
	v_fmac_f32_e32 v26, v10, v13
	v_fmac_f32_e32 v210, v9, v12
	v_fma_f32 v12, v8, v12, v26
	v_fma_f32 v13, v8, v13, v210
	v_fmac_f32_e32 v27, v10, v13
	v_fmac_f32_e32 v211, v9, v12
	v_fma_f32 v12, v8, v12, v27
	v_fma_f32 v13, v8, v13, v211
	v_fmac_f32_e32 v40, v10, v13
	v_fmac_f32_e32 v224, v9, v12
	v_fma_f32 v12, v8, v12, v40
	v_fma_f32 v13, v8, v13, v224
	v_fmac_f32_e32 v41, v10, v13
	v_fmac_f32_e32 v225, v9, v12
	v_fma_f32 v12, v8, v12, v41
	v_fma_f32 v13, v8, v13, v225
	v_fmac_f32_e32 v42, v10, v13
	v_fmac_f32_e32 v226, v9, v12
	v_fma_f32 v12, v8, v12, v42
	v_fma_f32 v13, v8, v13, v226
	v_fmac_f32_e32 v43, v10, v13
	v_fmac_f32_e32 v227, v9, v12
	v_fma_f32 v12, v8, v12, v43
	v_fma_f32 v13, v8, v13, v227
	v_fmac_f32_e32 v28, v10, v13
	v_fmac_f32_e32 v212, v9, v12
	v_fma_f32 v12, v8, v12, v28
	v_fma_f32 v13, v8, v13, v212
	v_fmac_f32_e32 v29, v10, v13
	v_fmac_f32_e32 v213, v9, v12
	v_fma_f32 v12, v8, v12, v29
	v_fma_f32 v13, v8, v13, v213
	v_fmac_f32_e32 v30, v10, v13
	v_fmac_f32_e32 v214, v9, v12
	v_fma_f32 v12, v8, v12, v30
	v_fma_f32 v13, v8, v13, v214
	v_fmac_f32_e32 v31, v10, v13
	v_fmac_f32_e32 v215, v9, v12
	v_fma_f32 v12, v8, v12, v31
	v_fma_f32 v13, v8, v13, v215
	v_fmac_f32_e32 v44, v10, v13
	v_fmac_f32_e32 v228, v9, v12
	v_fma_f32 v12, v8, v12, v44
	v_fma_f32 v13, v8, v13, v228
	v_fmac_f32_e32 v45, v10, v13
	v_fmac_f32_e32 v229, v9, v12
	v_fma_f32 v12, v8, v12, v45
	v_fma_f32 v13, v8, v13, v229
	v_fmac_f32_e32 v46, v10, v13
	v_fmac_f32_e32 v230, v9, v12
	v_fma_f32 v12, v8, v12, v46
	v_fma_f32 v13, v8, v13, v230
	v_fmac_f32_e32 v47, v10, v13
	v_fmac_f32_e32 v231, v9, v12
	v_fma_f32 v12, v8, v12, v47
	v_fma_f32 v13, v8, v13, v231
	s_nop 0
	global_store_dwordx2 v7, v[12:13], s[48:49]
	s_add_u32 s48, s48, 0x100000
	s_addc_u32 s49, s49, 0
	v_mov_b32_e32 v12, 0
	v_mov_b32_e32 v13, 0
	s_waitcnt vmcnt(3)
; #define LDS_WAIT() asm volatile("s_waitcnt lgkmcnt(0)" ::: "memory")
; __device__ __forceinline__ void p5_phase(Frame& F) {
;     ...
;         float sr = 0.f, si = 0.f;
; #pragma unroll
;         for (int sub = 0; sub < 4; ++sub) {
;             ssm_bu16(afr[sub], bf, bubuf, F.lane);
; #pragma unroll
;             for (int tt = 0; tt < 16; ++tt) { const float bur = bubuf[tt * BUP + F.lane], bui = bubuf[tt * BUP + 64 + F.lane];
;                 const float nr = fmaf(ab.x, sr, fmaf(-ab.y, si, bur)), ni = fmaf(ab.x, si, fmaf(ab.y, sr, bui)); sr = nr; si = ni; }
;             LDS_WAIT(); asm volatile("" ::: "memory");
;         }
	v_mfma_f32_32x32x16_bf16 v[16:31], v[108:111], v[48:51], 0
	v_mfma_f32_32x32x16_bf16 v[32:47], v[108:111], v[52:55], 0
	v_mfma_f32_32x32x16_bf16 v[200:215], v[108:111], v[56:59], 0
	v_mfma_f32_32x32x16_bf16 v[216:231], v[108:111], v[60:63], 0
	v_mfma_f32_32x32x16_bf16 v[16:31], v[108:111], v[64:67], v[16:31]
	v_mfma_f32_32x32x16_bf16 v[32:47], v[108:111], v[68:71], v[32:47]
	v_mfma_f32_32x32x16_bf16 v[200:215], v[108:111], v[72:75], v[200:215]
	v_mfma_f32_32x32x16_bf16 v[216:231], v[108:111], v[76:79], v[216:231]
	s_nop 3
	v_permlane32_swap_b32_e32 v112, v128
	v_permlane32_swap_b32_e32 v144, v160
	v_permlane32_swap_b32_e32 v113, v129
	v_permlane32_swap_b32_e32 v145, v161
	v_permlane32_swap_b32_e32 v114, v130
	v_permlane32_swap_b32_e32 v146, v162
	v_permlane32_swap_b32_e32 v115, v131
	v_permlane32_swap_b32_e32 v147, v163
	v_permlane32_swap_b32_e32 v116, v132
	v_permlane32_swap_b32_e32 v148, v164
	v_permlane32_swap_b32_e32 v117, v133
	v_permlane32_swap_b32_e32 v149, v165
	v_permlane32_swap_b32_e32 v118, v134
	v_permlane32_swap_b32_e32 v150, v166
	v_permlane32_swap_b32_e32 v119, v135
	v_permlane32_swap_b32_e32 v151, v167
	v_permlane32_swap_b32_e32 v120, v136
	v_permlane32_swap_b32_e32 v152, v168
	v_permlane32_swap_b32_e32 v121, v137
	v_permlane32_swap_b32_e32 v153, v169
	v_permlane32_swap_b32_e32 v122, v138
	v_permlane32_swap_b32_e32 v154, v170
	v_permlane32_swap_b32_e32 v123, v139
	v_permlane32_swap_b32_e32 v155, v171
	v_permlane32_swap_b32_e32 v124, v140
	v_permlane32_swap_b32_e32 v156, v172
	v_permlane32_swap_b32_e32 v125, v141
	v_permlane32_swap_b32_e32 v157, v173
	v_permlane32_swap_b32_e32 v126, v142
	v_permlane32_swap_b32_e32 v158, v174
	v_permlane32_swap_b32_e32 v127, v143
	v_permlane32_swap_b32_e32 v159, v175
	v_fmac_f32_e32 v112, v10, v13
	v_fmac_f32_e32 v144, v9, v12
	v_fma_f32 v12, v8, v12, v112
	v_fma_f32 v13, v8, v13, v144
	v_fmac_f32_e32 v113, v10, v13
	v_fmac_f32_e32 v145, v9, v12
	v_fma_f32 v12, v8, v12, v113
	v_fma_f32 v13, v8, v13, v145
	v_fmac_f32_e32 v114, v10, v13
	v_fmac_f32_e32 v146, v9, v12
	v_fma_f32 v12, v8, v12, v114
	v_fma_f32 v13, v8, v13, v146
	v_fmac_f32_e32 v115, v10, v13
	v_fmac_f32_e32 v147, v9, v12
	v_fma_f32 v12, v8, v12, v115
	v_fma_f32 v13, v8, v13, v147
	v_fmac_f32_e32 v128, v10, v13
	v_fmac_f32_e32 v160, v9, v12
	v_fma_f32 v12, v8, v12, v128
	v_fma_f32 v13, v8, v13, v160
	v_fmac_f32_e32 v129, v10, v13
	v_fmac_f32_e32 v161, v9, v12
	v_fma_f32 v12, v8, v12, v129
	v_fma_f32 v13, v8, v13, v161
	v_fmac_f32_e32 v130, v10, v13
	v_fmac_f32_e32 v162, v9, v12
	v_fma_f32 v12, v8, v12, v130
	v_fma_f32 v13, v8, v13, v162
	v_fmac_f32_e32 v131, v10, v13
	v_fmac_f32_e32 v163, v9, v12
	v_fma_f32 v12, v8, v12, v131
	v_fma_f32 v13, v8, v13, v163
	v_fmac_f32_e32 v116, v10, v13
	v_fmac_f32_e32 v148, v9, v12
	v_fma_f32 v12, v8, v12, v116
	v_fma_f32 v13, v8, v13, v148
	v_fmac_f32_e32 v117, v10, v13
	v_fmac_f32_e32 v149, v9, v12
	v_fma_f32 v12, v8, v12, v117
	v_fma_f32 v13, v8, v13, v149
	v_fmac_f32_e32 v118, v10, v13
	v_fmac_f32_e32 v150, v9, v12
	v_fma_f32 v12, v8, v12, v118
	v_fma_f32 v13, v8, v13, v150
	v_fmac_f32_e32 v119, v10, v13
	v_fmac_f32_e32 v151, v9, v12
	v_fma_f32 v12, v8, v12, v119
	v_fma_f32 v13, v8, v13, v151
	v_fmac_f32_e32 v132, v10, v13
	v_fmac_f32_e32 v164, v9, v12
	v_fma_f32 v12, v8, v12, v132
	v_fma_f32 v13, v8, v13, v164
	v_fmac_f32_e32 v133, v10, v13
	v_fmac_f32_e32 v165, v9, v12
	v_fma_f32 v12, v8, v12, v133
	v_fma_f32 v13, v8, v13, v165
	v_fmac_f32_e32 v134, v10, v13
	v_fmac_f32_e32 v166, v9, v12
	v_fma_f32 v12, v8, v12, v134
	v_fma_f32 v13, v8, v13, v166
	v_fmac_f32_e32 v135, v10, v13
	v_fmac_f32_e32 v167, v9, v12
	v_fma_f32 v12, v8, v12, v135
	v_fma_f32 v13, v8, v13, v167
	v_fmac_f32_e32 v120, v10, v13
	v_fmac_f32_e32 v152, v9, v12
	v_fma_f32 v12, v8, v12, v120
	v_fma_f32 v13, v8, v13, v152
	v_fmac_f32_e32 v121, v10, v13
	v_fmac_f32_e32 v153, v9, v12
	v_fma_f32 v12, v8, v12, v121
	v_fma_f32 v13, v8, v13, v153
	v_fmac_f32_e32 v122, v10, v13
	v_fmac_f32_e32 v154, v9, v12
	v_fma_f32 v12, v8, v12, v122
	v_fma_f32 v13, v8, v13, v154
	v_fmac_f32_e32 v123, v10, v13
	v_fmac_f32_e32 v155, v9, v12
	v_fma_f32 v12, v8, v12, v123
	v_fma_f32 v13, v8, v13, v155
	v_fmac_f32_e32 v136, v10, v13
	v_fmac_f32_e32 v168, v9, v12
	v_fma_f32 v12, v8, v12, v136
	v_fma_f32 v13, v8, v13, v168
	v_fmac_f32_e32 v137, v10, v13
	v_fmac_f32_e32 v169, v9, v12
	v_fma_f32 v12, v8, v12, v137
	v_fma_f32 v13, v8, v13, v169
	v_fmac_f32_e32 v138, v10, v13
	v_fmac_f32_e32 v170, v9, v12
	v_fma_f32 v12, v8, v12, v138
	v_fma_f32 v13, v8, v13, v170
	v_fmac_f32_e32 v139, v10, v13
	v_fmac_f32_e32 v171, v9, v12
	v_fma_f32 v12, v8, v12, v139
	v_fma_f32 v13, v8, v13, v171
	v_fmac_f32_e32 v124, v10, v13
	v_fmac_f32_e32 v156, v9, v12
	v_fma_f32 v12, v8, v12, v124
	v_fma_f32 v13, v8, v13, v156
	v_fmac_f32_e32 v125, v10, v13
	v_fmac_f32_e32 v157, v9, v12
	v_fma_f32 v12, v8, v12, v125
	v_fma_f32 v13, v8, v13, v157
	v_fmac_f32_e32 v126, v10, v13
	v_fmac_f32_e32 v158, v9, v12
	v_fma_f32 v12, v8, v12, v126
	v_fma_f32 v13, v8, v13, v158
	v_fmac_f32_e32 v127, v10, v13
	v_fmac_f32_e32 v159, v9, v12
	v_fma_f32 v12, v8, v12, v127
	v_fma_f32 v13, v8, v13, v159
	v_fmac_f32_e32 v140, v10, v13
	v_fmac_f32_e32 v172, v9, v12
	v_fma_f32 v12, v8, v12, v140
	v_fma_f32 v13, v8, v13, v172
	v_fmac_f32_e32 v141, v10, v13
	v_fmac_f32_e32 v173, v9, v12
	v_fma_f32 v12, v8, v12, v141
	v_fma_f32 v13, v8, v13, v173
; #define LAS __attribute__((address_space(3)))
; #define LDS_WAIT() asm volatile("s_waitcnt lgkmcnt(0)" ::: "memory")
; #define MFMA_PIN(a, b) do { __builtin_amdgcn_sched_barrier(0); asm volatile("" :: "v"(a), "v"(b)); } while (0)
; #define MFMA_SETTLE() do { __builtin_amdgcn_sched_barrier(0); asm volatile("s_nop 15"); __builtin_amdgcn_sched_barrier(0); } while (0)
; __device__ __forceinline__ void ssm_bu16(const bf16x8 afr, const bf16x8 (&bf)[8], LAS float* bubuf, int lane) {
;     LAS float* wp = bubuf + (4 * (lane >> 4)) * BUP + (lane & 15);
;     f32x4 d[8];
; #pragma unroll
;     for (int cb = 0; cb < 8; ++cb) { d[cb] = __builtin_amdgcn_mfma_f32_16x16x32_bf16(afr, bf[cb], (f32x4){0.f, 0.f, 0.f, 0.f}, 0, 0, 0); MFMA_PIN(afr, bf[cb]); }
;     MFMA_SETTLE();
; __device__ __forceinline__ void p5_phase(Frame& F) {
;     ...
;         float sr = 0.f, si = 0.f;
; #pragma unroll
;         for (int sub = 0; sub < 4; ++sub) {
;             ssm_bu16(afr[sub], bf, bubuf, F.lane);
; #pragma unroll
;             for (int tt = 0; tt < 16; ++tt) { const float bur = bubuf[tt * BUP + F.lane], bui = bubuf[tt * BUP + 64 + F.lane];
;                 const float nr = fmaf(ab.x, sr, fmaf(-ab.y, si, bur)), ni = fmaf(ab.x, si, fmaf(ab.y, sr, bui)); sr = nr; si = ni; }
;             LDS_WAIT(); asm volatile("" ::: "memory");
;         }
;         ((f32x2*)(F.ws + WS_E))[(size_t)it * NST + F.lane] = (f32x2){sr, si};
	v_fmac_f32_e32 v142, v10, v13
	v_fmac_f32_e32 v174, v9, v12
	v_fma_f32 v12, v8, v12, v142
	v_fma_f32 v13, v8, v13, v174
	v_fmac_f32_e32 v143, v10, v13
	v_fmac_f32_e32 v175, v9, v12
	v_fma_f32 v12, v8, v12, v143
	v_fma_f32 v13, v8, v13, v175
	s_nop 15
	s_nop 15
	s_nop 3
	v_permlane32_swap_b32_e32 v16, v32
	v_permlane32_swap_b32_e32 v200, v216
	v_permlane32_swap_b32_e32 v17, v33
	v_permlane32_swap_b32_e32 v201, v217
	v_permlane32_swap_b32_e32 v18, v34
	v_permlane32_swap_b32_e32 v202, v218
	v_permlane32_swap_b32_e32 v19, v35
	v_permlane32_swap_b32_e32 v203, v219
	v_permlane32_swap_b32_e32 v20, v36
	v_permlane32_swap_b32_e32 v204, v220
	v_permlane32_swap_b32_e32 v21, v37
	v_permlane32_swap_b32_e32 v205, v221
	v_permlane32_swap_b32_e32 v22, v38
	v_permlane32_swap_b32_e32 v206, v222
	v_permlane32_swap_b32_e32 v23, v39
	v_permlane32_swap_b32_e32 v207, v223
	v_permlane32_swap_b32_e32 v24, v40
	v_permlane32_swap_b32_e32 v208, v224
	v_permlane32_swap_b32_e32 v25, v41
	v_permlane32_swap_b32_e32 v209, v225
	v_permlane32_swap_b32_e32 v26, v42
	v_permlane32_swap_b32_e32 v210, v226
	v_permlane32_swap_b32_e32 v27, v43
	v_permlane32_swap_b32_e32 v211, v227
	v_permlane32_swap_b32_e32 v28, v44
	v_permlane32_swap_b32_e32 v212, v228
	v_permlane32_swap_b32_e32 v29, v45
	v_permlane32_swap_b32_e32 v213, v229
	v_permlane32_swap_b32_e32 v30, v46
	v_permlane32_swap_b32_e32 v214, v230
	v_permlane32_swap_b32_e32 v31, v47
	v_permlane32_swap_b32_e32 v215, v231
	v_fmac_f32_e32 v16, v10, v13
	v_fmac_f32_e32 v200, v9, v12
	v_fma_f32 v12, v8, v12, v16
	v_fma_f32 v13, v8, v13, v200
	v_fmac_f32_e32 v17, v10, v13
	v_fmac_f32_e32 v201, v9, v12
	v_fma_f32 v12, v8, v12, v17
	v_fma_f32 v13, v8, v13, v201
	v_fmac_f32_e32 v18, v10, v13
	v_fmac_f32_e32 v202, v9, v12
	v_fma_f32 v12, v8, v12, v18
	v_fma_f32 v13, v8, v13, v202
	v_fmac_f32_e32 v19, v10, v13
	v_fmac_f32_e32 v203, v9, v12
	v_fma_f32 v12, v8, v12, v19
	v_fma_f32 v13, v8, v13, v203
	v_fmac_f32_e32 v32, v10, v13
	v_fmac_f32_e32 v216, v9, v12
	v_fma_f32 v12, v8, v12, v32
	v_fma_f32 v13, v8, v13, v216
	v_fmac_f32_e32 v33, v10, v13
	v_fmac_f32_e32 v217, v9, v12
	v_fma_f32 v12, v8, v12, v33
	v_fma_f32 v13, v8, v13, v217
	v_fmac_f32_e32 v34, v10, v13
	v_fmac_f32_e32 v218, v9, v12
	v_fma_f32 v12, v8, v12, v34
	v_fma_f32 v13, v8, v13, v218
	v_fmac_f32_e32 v35, v10, v13
	v_fmac_f32_e32 v219, v9, v12
	v_fma_f32 v12, v8, v12, v35
	v_fma_f32 v13, v8, v13, v219
	v_fmac_f32_e32 v20, v10, v13
	v_fmac_f32_e32 v204, v9, v12
	v_fma_f32 v12, v8, v12, v20
	v_fma_f32 v13, v8, v13, v204
	v_fmac_f32_e32 v21, v10, v13
	v_fmac_f32_e32 v205, v9, v12
	v_fma_f32 v12, v8, v12, v21
	v_fma_f32 v13, v8, v13, v205
	v_fmac_f32_e32 v22, v10, v13
	v_fmac_f32_e32 v206, v9, v12
	v_fma_f32 v12, v8, v12, v22
	v_fma_f32 v13, v8, v13, v206
	v_fmac_f32_e32 v23, v10, v13
	v_fmac_f32_e32 v207, v9, v12
	v_fma_f32 v12, v8, v12, v23
	v_fma_f32 v13, v8, v13, v207
	v_fmac_f32_e32 v36, v10, v13
	v_fmac_f32_e32 v220, v9, v12
	v_fma_f32 v12, v8, v12, v36
	v_fma_f32 v13, v8, v13, v220
	v_fmac_f32_e32 v37, v10, v13
	v_fmac_f32_e32 v221, v9, v12
	v_fma_f32 v12, v8, v12, v37
	v_fma_f32 v13, v8, v13, v221
	v_fmac_f32_e32 v38, v10, v13
	v_fmac_f32_e32 v222, v9, v12
	v_fma_f32 v12, v8, v12, v38
	v_fma_f32 v13, v8, v13, v222
	v_fmac_f32_e32 v39, v10, v13
	v_fmac_f32_e32 v223, v9, v12
	v_fma_f32 v12, v8, v12, v39
	v_fma_f32 v13, v8, v13, v223
	v_fmac_f32_e32 v24, v10, v13
	v_fmac_f32_e32 v208, v9, v12
	v_fma_f32 v12, v8, v12, v24
	v_fma_f32 v13, v8, v13, v208
	v_fmac_f32_e32 v25, v10, v13
	v_fmac_f32_e32 v209, v9, v12
	v_fma_f32 v12, v8, v12, v25
	v_fma_f32 v13, v8, v13, v209
	v_fmac_f32_e32 v26, v10, v13
	v_fmac_f32_e32 v210, v9, v12
	v_fma_f32 v12, v8, v12, v26
	v_fma_f32 v13, v8, v13, v210
	v_fmac_f32_e32 v27, v10, v13
	v_fmac_f32_e32 v211, v9, v12
	v_fma_f32 v12, v8, v12, v27
	v_fma_f32 v13, v8, v13, v211
	v_fmac_f32_e32 v40, v10, v13
	v_fmac_f32_e32 v224, v9, v12
	v_fma_f32 v12, v8, v12, v40
	v_fma_f32 v13, v8, v13, v224
	v_fmac_f32_e32 v41, v10, v13
	v_fmac_f32_e32 v225, v9, v12
	v_fma_f32 v12, v8, v12, v41
	v_fma_f32 v13, v8, v13, v225
	v_fmac_f32_e32 v42, v10, v13
	v_fmac_f32_e32 v226, v9, v12
	v_fma_f32 v12, v8, v12, v42
	v_fma_f32 v13, v8, v13, v226
	v_fmac_f32_e32 v43, v10, v13
	v_fmac_f32_e32 v227, v9, v12
	v_fma_f32 v12, v8, v12, v43
	v_fma_f32 v13, v8, v13, v227
	v_fmac_f32_e32 v28, v10, v13
	v_fmac_f32_e32 v212, v9, v12
	v_fma_f32 v12, v8, v12, v28
	v_fma_f32 v13, v8, v13, v212
	v_fmac_f32_e32 v29, v10, v13
	v_fmac_f32_e32 v213, v9, v12
	v_fma_f32 v12, v8, v12, v29
	v_fma_f32 v13, v8, v13, v213
	v_fmac_f32_e32 v30, v10, v13
	v_fmac_f32_e32 v214, v9, v12
	v_fma_f32 v12, v8, v12, v30
	v_fma_f32 v13, v8, v13, v214
	v_fmac_f32_e32 v31, v10, v13
	v_fmac_f32_e32 v215, v9, v12
	v_fma_f32 v12, v8, v12, v31
	v_fma_f32 v13, v8, v13, v215
	v_fmac_f32_e32 v44, v10, v13
	v_fmac_f32_e32 v228, v9, v12
	v_fma_f32 v12, v8, v12, v44
	v_fma_f32 v13, v8, v13, v228
	v_fmac_f32_e32 v45, v10, v13
	v_fmac_f32_e32 v229, v9, v12
	v_fma_f32 v12, v8, v12, v45
	v_fma_f32 v13, v8, v13, v229
	v_fmac_f32_e32 v46, v10, v13
	v_fmac_f32_e32 v230, v9, v12
	v_fma_f32 v12, v8, v12, v46
	v_fma_f32 v13, v8, v13, v230
	v_fmac_f32_e32 v47, v10, v13
	v_fmac_f32_e32 v231, v9, v12
	v_fma_f32 v12, v8, v12, v47
	v_fma_f32 v13, v8, v13, v231
	s_nop 0
	global_store_dwordx2 v7, v[12:13], s[48:49]
	s_add_u32 s48, s48, 0x100000
	s_addc_u32 s49, s49, 0
